# v49 plus EpiUp epilogue: vmcnt waits that guard the sample-tile conv-state loads no longer run on prompt tiles (where they only drained the just-issued ACT stores): vmcnt part removed in the no-load b
# baseline (speedup 1.0000x reference)
; #define LAS __attribute__((address_space(3)))
;     __device__ __forceinline__ void operator()(const f32x4 (&acc_)[2][2][4][2], const pg8::Unit& u, int wr, int wc, int fr, int fq) const {
;     ...
;                     if (!prompt) { const float* ps = past + (size_t)((blk0 - MP) >> 6) * 2 * DFF2 + cc; hm2[bj] = *(const f32x4*)ps; hm1[bj] = *(const f32x4*)(ps + DFF2); }
;                     else if (ai == 0 && wr == 0) { hm1[bj] = (f32x4){0.f, 0.f, 0.f, 0.f}; hm2[bj] = hm1[bj]; }
;                     else { const int pb = ai * 2 + wr - 1; const LAS float* s = hl + (((pb * 4 + wc) * 2 + 0) * 4 + fq) * 16 + bj * 8 + 4 * eh; hm2[bj] = *(const LAS f32x4*)s; hm1[bj] = *(const LAS f32x4*)(s + 64); }
.LBB0_1818:
	v_and_b32_e32 v146, 0x3ffffff0, v146
	v_lshl_add_u32 v191, v146, 2, s57
	v_cndmask_b32_e64 v146, 0, 1, s[26:27]
	s_andn2_b64 vcc, exec, s[2:3]
	v_cmp_ne_u32_e64 s[14:15], 1, v146
	s_cbranch_vccnz .LBB0_1821
	v_mov_b32_e32 v165, 0
	s_and_b64 vcc, exec, s[14:15]
	v_mov_b32_e32 v164, 0
	v_mov_b32_e32 v163, 0
	v_mov_b32_e32 v162, 0
	v_mov_b32_e32 v169, 0
	v_mov_b32_e32 v168, 0
	v_mov_b32_e32 v167, 0
	v_mov_b32_e32 v166, 0
	s_cbranch_vccnz .LBB0_1821
	v_add_u32_e32 v146, 0xfffff800, v191
	v_add_u32_e32 v147, 0xfffff900, v191
	ds_read_b128 v[166:169], v146
	ds_read_b128 v[162:165], v147

; #define LAS __attribute__((address_space(3)))
;     __device__ __forceinline__ void operator()(const f32x4 (&acc_)[2][2][4][2], const pg8::Unit& u, int wr, int wc, int fr, int fq) const {
;     ...
;                 f32x4 w[2][3], bia[2], hm1[2], hm2[2];
; #pragma unroll
;                 for (int bj = 0; bj < 2; ++bj) {
;                     const int cc = bj * DFF + ch + 4 * eh;
; #pragma unroll
;                     for (int j = 0; j < 3; ++j) w[bj][j] = *(const LAS f32x4*)(cwl + (2 * j + bj) * 128 + 4 * eh);
;                     bia[bj] = *(const LAS f32x4*)(cwl + (6 + bj) * 128 + 4 * eh);
;                     if (!prompt) { const float* ps = past + (size_t)((blk0 - MP) >> 6) * 2 * DFF2 + cc; hm2[bj] = *(const f32x4*)ps; hm1[bj] = *(const f32x4*)(ps + DFF2); }
;                     else if (ai == 0 && wr == 0) { hm1[bj] = (f32x4){0.f, 0.f, 0.f, 0.f}; hm2[bj] = hm1[bj]; }
;                     else { const int pb = ai * 2 + wr - 1; const LAS float* s = hl + (((pb * 4 + wc) * 2 + 0) * 4 + fq) * 16 + bj * 8 + 4 * eh; hm2[bj] = *(const LAS f32x4*)s; hm1[bj] = *(const LAS f32x4*)(s + 64); }
;                 }
;                 u32x2 pk[4]; f32x4 pr1[2], pr2[2];
; #pragma unroll
;                 for (int bj = 0; bj < 2; ++bj)
; #pragma unroll
;                     for (int e = 0; e < 4; ++e) { pr1[bj][e] = hm1[bj][e]; pr2[bj][e] = (fr == 0) ? hm2[bj][e] : hm1[bj][e]; }
; #pragma unroll
;                 for (int m = 0; m < 4; ++m) {
;                     f32x4 c[2];
; #pragma unroll
;                     for (int bj = 0; bj < 2; ++bj) {
;                         const f32x4 h0 = acc[ai][bj][m][eh]; f32x4 p1, p2;
; #pragma unroll
;                         for (int e = 0; e < 4; ++e) {
;                             const float r1 = dpp_ror1(h0[e]), r2 = dpp_ror2(h0[e]);
;                             p1[e] = (fr >= 1) ? r1 : pr1[bj][e]; p2[e] = (fr >= 2) ? r2 : pr2[bj][e];
;                             pr1[bj][e] = r1; pr2[bj][e] = r2;
;                         }
;                         c[bj] = bia[bj] + w[bj][0] * p2 + w[bj][1] * p1 + w[bj][2] * h0;
;                     }
;                     f32x4 o;
; #pragma unroll
;                     for (int e = 0; e < 4; ++e) o[e] = silu_f(c[0][e]) * c[1][e];
;                     pk[m].x = cvt_pk_bf16(o[0], o[1]); pk[m].y = cvt_pk_bf16(o[2], o[3]);
;                 }
; #pragma unroll
.LBB0_1823:
	s_andn2_b64 vcc, exec, s[2:3]
	s_cbranch_vccnz .LBB0_1828
	s_and_b64 vcc, exec, s[14:15]
	s_mov_b64 s[2:3], -1
	s_cbranch_vccnz .LBB0_1826
	v_add_u32_e32 v170, 0xfffff820, v191
	v_add_u32_e32 v171, 0xfffff920, v191
	ds_read_b128 v[174:177], v170
	ds_read_b128 v[170:173], v171
	s_mov_b64 s[2:3], 0
.LBB0_1826:
	s_andn2_b64 vcc, exec, s[2:3]
	s_cbranch_vccnz .LBB0_1828
	s_waitcnt lgkmcnt(0)
	v_mov_b32_e32 v173, 0
	v_mov_b32_e32 v172, v173
	v_mov_b32_e32 v171, v173
	v_mov_b32_e32 v170, v173
	v_mov_b32_e32 v177, v173
	v_mov_b32_e32 v176, v173
	v_mov_b32_e32 v175, v173
	v_mov_b32_e32 v174, v173
.LBB0_1828:
	v_mov_b32_e32 v212, v199
	v_cmp_eq_u32_e64 s[10:11], 0, v210
	v_pk_mul_f32 v[206:207], v[102:103], v[198:199] op_sel_hi:[1,0]
	v_pk_mul_f32 v[102:103], v[100:101], v[212:213] op_sel_hi:[1,0]
	s_waitcnt lgkmcnt(0)
	s_and_b64 vcc, exec, s[8:9]
	s_cbranch_vccnz .Leu_j1828
	s_waitcnt vmcnt(0)
.Leu_j1828:
	v_cndmask_b32_e64 v101, v162, v166, s[10:11]
	v_cndmask_b32_e64 v166, v164, v168, s[10:11]
	v_cndmask_b32_e64 v168, v170, v174, s[10:11]
	v_cndmask_b32_e64 v174, v172, v176, s[10:11]
	v_mov_b32_dpp v176, v126 row_ror:1 row_mask:0xf bank_mask:0xf bound_ctrl:1
	v_cmp_lt_u32_e64 s[12:13], 1, v210
	v_mov_b32_dpp v214, v128 row_ror:1 row_mask:0xf bank_mask:0xf bound_ctrl:1
	v_mov_b32_dpp v215, v128 row_ror:2 row_mask:0xf bank_mask:0xf bound_ctrl:1
	v_pk_mul_f32 v[204:205], v[104:105], v[198:199] op_sel_hi:[1,0]
	v_pk_mul_f32 v[104:105], v[108:109], v[212:213] op_sel_hi:[1,0]
	v_pk_mul_f32 v[106:107], v[106:107], v[212:213] op_sel_hi:[1,0]
	v_pk_mul_f32 v[98:99], v[98:99], v[212:213] op_sel_hi:[1,0]
	v_cndmask_b32_e64 v109, v163, v167, s[10:11]
	v_cndmask_b32_e64 v167, v165, v169, s[10:11]
	v_cndmask_b32_e64 v169, v171, v175, s[10:11]
	v_cndmask_b32_e64 v175, v173, v177, s[10:11]
	v_mov_b32_dpp v177, v126 row_ror:2 row_mask:0xf bank_mask:0xf bound_ctrl:1
	v_cndmask_b32_e64 v100, v176, v162, s[10:11]
	v_mov_b32_dpp v212, v127 row_ror:1 row_mask:0xf bank_mask:0xf bound_ctrl:1
	v_mov_b32_dpp v213, v127 row_ror:2 row_mask:0xf bank_mask:0xf bound_ctrl:1
	v_cndmask_b32_e64 v162, v214, v164, s[10:11]
	v_cndmask_b32_e64 v164, v166, v215, s[12:13]
	v_mov_b32_dpp v166, v129 row_ror:1 row_mask:0xf bank_mask:0xf bound_ctrl:1
	v_mov_b32_dpp v216, v129 row_ror:2 row_mask:0xf bank_mask:0xf bound_ctrl:1
	v_cndmask_b32_e64 v108, v101, v177, s[12:13]
	v_cndmask_b32_e64 v101, v212, v163, s[10:11]
	v_cndmask_b32_e64 v109, v109, v213, s[12:13]
	v_cndmask_b32_e64 v163, v166, v165, s[10:11]
	v_cndmask_b32_e64 v165, v167, v216, s[12:13]
	v_pk_fma_f32 v[164:165], v[140:141], v[164:165], v[144:145]
	v_pk_fma_f32 v[108:109], v[138:139], v[108:109], v[142:143]
	v_mov_b32_dpp v217, v122 row_ror:2 row_mask:0xf bank_mask:0xf bound_ctrl:1
	v_pk_fma_f32 v[100:101], v[134:135], v[100:101], v[108:109]
	v_pk_fma_f32 v[108:109], v[136:137], v[162:163], v[164:165]
	v_mov_b32_dpp v167, v122 row_ror:1 row_mask:0xf bank_mask:0xf bound_ctrl:1
	v_pk_fma_f32 v[108:109], v[128:129], v[132:133], v[108:109]
	v_cndmask_b32_e64 v128, v168, v217, s[12:13]
	v_mov_b32_dpp v168, v123 row_ror:1 row_mask:0xf bank_mask:0xf bound_ctrl:1
	v_pk_fma_f32 v[100:101], v[126:127], v[130:131], v[100:101]
	v_cndmask_b32_e64 v126, v167, v170, s[10:11]
	v_mov_b32_dpp v170, v123 row_ror:2 row_mask:0xf bank_mask:0xf bound_ctrl:1
	v_cndmask_b32_e64 v127, v168, v171, s[10:11]
	v_mov_b32_dpp v171, v124 row_ror:2 row_mask:0xf bank_mask:0xf bound_ctrl:1
	v_cndmask_b32_e64 v129, v169, v170, s[12:13]
	v_mov_b32_dpp v169, v124 row_ror:1 row_mask:0xf bank_mask:0xf bound_ctrl:1
	v_cndmask_b32_e64 v164, v174, v171, s[12:13]
	v_mov_b32_dpp v174, v125 row_ror:2 row_mask:0xf bank_mask:0xf bound_ctrl:1
	v_cndmask_b32_e64 v162, v169, v172, s[10:11]
	v_mov_b32_dpp v172, v125 row_ror:1 row_mask:0xf bank_mask:0xf bound_ctrl:1
	v_cndmask_b32_e64 v165, v175, v174, s[12:13]
	v_cndmask_b32_e64 v163, v172, v173, s[10:11]
	v_pk_fma_f32 v[164:165], v[156:157], v[164:165], v[160:161]
	v_pk_fma_f32 v[128:129], v[154:155], v[128:129], v[158:159]
	v_pk_mul_f32 v[112:113], v[112:113], v[198:199] op_sel_hi:[1,0]
	v_pk_fma_f32 v[126:127], v[150:151], v[126:127], v[128:129]
	v_pk_fma_f32 v[128:129], v[152:153], v[162:163], v[164:165]
	v_mul_f32_e32 v162, 0xbfb8aa3b, v100
	v_mul_f32_e32 v163, 0xbfb8aa3b, v101
	v_exp_f32_e32 v162, v162
	v_exp_f32_e32 v163, v163
	v_pk_fma_f32 v[124:125], v[124:125], v[148:149], v[128:129]
	v_pk_mul_f32 v[110:111], v[110:111], v[198:199] op_sel_hi:[1,0]
	v_add_f32_e32 v128, 1.0, v162
	v_add_f32_e32 v129, 1.0, v163
	v_mul_f32_e32 v162, 0xbfb8aa3b, v108
	v_mul_f32_e32 v163, 0xbfb8aa3b, v109
	v_exp_f32_e32 v162, v162
	v_exp_f32_e32 v163, v163
	v_rcp_f32_e32 v128, v128
	v_rcp_f32_e32 v129, v129
	v_add_f32_e32 v162, 1.0, v162
	v_add_f32_e32 v163, 1.0, v163
	v_rcp_f32_e32 v162, v162
	v_rcp_f32_e32 v163, v163
	v_pk_fma_f32 v[122:123], v[122:123], v[146:147], v[126:127]
	v_pk_mul_f32 v[100:101], v[100:101], v[128:129]
	v_mov_b32_dpp v129, v110 row_ror:2 row_mask:0xf bank_mask:0xf bound_ctrl:1
	v_pk_mul_f32 v[108:109], v[108:109], v[162:163]
	v_mov_b32_dpp v163, v111 row_ror:2 row_mask:0xf bank_mask:0xf bound_ctrl:1
	v_mov_b32_dpp v165, v112 row_ror:2 row_mask:0xf bank_mask:0xf bound_ctrl:1
	v_mov_b32_dpp v175, v113 row_ror:2 row_mask:0xf bank_mask:0xf bound_ctrl:1
	v_pk_mul_f32 v[100:101], v[100:101], v[122:123]
	v_pk_mul_f32 v[108:109], v[108:109], v[124:125]
	v_mov_b32_dpp v128, v110 row_ror:1 row_mask:0xf bank_mask:0xf bound_ctrl:1
	v_cndmask_b32_e64 v122, v177, v129, s[12:13]
	v_mov_b32_dpp v162, v111 row_ror:1 row_mask:0xf bank_mask:0xf bound_ctrl:1
	v_cndmask_b32_e64 v123, v213, v163, s[12:13]
; __device__ __forceinline__ unsigned cvt_pk_bf16(float lo, float hi) { const f32x2 v = {lo, hi}; unsigned r = __builtin_bit_cast(unsigned, __builtin_convertvector(v, bf16x2_t)); asm volatile("" : "+v"(r)); return r; }
; __device__ __forceinline__ float silu_f(float x) { return x * __builtin_amdgcn_rcpf(1.0f + __expf(-x)); }
; __device__ __forceinline__ float dpp_ror1(float x) { return __builtin_bit_cast(float, __builtin_amdgcn_update_dpp(0, __builtin_bit_cast(int, x), 0x121, 0xf, 0xf, true)); }
; __device__ __forceinline__ float dpp_ror2(float x) { return __builtin_bit_cast(float, __builtin_amdgcn_update_dpp(0, __builtin_bit_cast(int, x), 0x122, 0xf, 0xf, true)); }
;     __device__ __forceinline__ void operator()(const f32x4 (&acc_)[2][2][4][2], const pg8::Unit& u, int wr, int wc, int fr, int fq) const {
;     ...
;                 for (int m = 0; m < 4; ++m) {
;                     f32x4 c[2];
; #pragma unroll
;                     for (int bj = 0; bj < 2; ++bj) {
;                         const f32x4 h0 = acc[ai][bj][m][eh]; f32x4 p1, p2;
; #pragma unroll
;                         for (int e = 0; e < 4; ++e) {
;                             const float r1 = dpp_ror1(h0[e]), r2 = dpp_ror2(h0[e]);
;                             p1[e] = (fr >= 1) ? r1 : pr1[bj][e]; p2[e] = (fr >= 2) ? r2 : pr2[bj][e];
;                             pr1[bj][e] = r1; pr2[bj][e] = r2;
;                         }
;                         c[bj] = bia[bj] + w[bj][0] * p2 + w[bj][1] * p1 + w[bj][2] * h0;
;                     }
;                     f32x4 o;
; #pragma unroll
;                     for (int e = 0; e < 4; ++e) o[e] = silu_f(c[0][e]) * c[1][e];
;                     pk[m].x = cvt_pk_bf16(o[0], o[1]); pk[m].y = cvt_pk_bf16(o[2], o[3]);
;                 }
	v_mov_b32_dpp v164, v112 row_ror:1 row_mask:0xf bank_mask:0xf bound_ctrl:1
	v_cndmask_b32_e64 v126, v215, v165, s[12:13]
	v_mov_b32_dpp v173, v113 row_ror:1 row_mask:0xf bank_mask:0xf bound_ctrl:1
	v_cndmask_b32_e64 v127, v216, v175, s[12:13]
	v_cvt_pk_bf16_f32 v100, v100, v101
	v_cvt_pk_bf16_f32 v101, v108, v109
	v_cndmask_b32_e64 v108, v128, v176, s[10:11]
	v_cndmask_b32_e64 v109, v162, v212, s[10:11]
	v_cndmask_b32_e64 v124, v164, v214, s[10:11]
	v_cndmask_b32_e64 v125, v173, v166, s[10:11]
	v_pk_fma_f32 v[122:123], v[138:139], v[122:123], v[142:143]
	v_pk_fma_f32 v[126:127], v[140:141], v[126:127], v[144:145]
	v_pk_fma_f32 v[108:109], v[134:135], v[108:109], v[122:123]
	v_pk_fma_f32 v[122:123], v[136:137], v[124:125], v[126:127]
	v_mov_b32_dpp v166, v206 row_ror:1 row_mask:0xf bank_mask:0xf bound_ctrl:1
	v_mov_b32_dpp v177, v207 row_ror:2 row_mask:0xf bank_mask:0xf bound_ctrl:1
	v_pk_fma_f32 v[108:109], v[110:111], v[130:131], v[108:109]
	v_pk_fma_f32 v[110:111], v[112:113], v[132:133], v[122:123]
	v_cndmask_b32_e64 v112, v166, v167, s[10:11]
	v_mov_b32_dpp v167, v207 row_ror:1 row_mask:0xf bank_mask:0xf bound_ctrl:1
	v_cndmask_b32_e64 v123, v170, v177, s[12:13]
	v_mov_b32_dpp v170, v204 row_ror:2 row_mask:0xf bank_mask:0xf bound_ctrl:1
	v_mov_b32_dpp v176, v206 row_ror:2 row_mask:0xf bank_mask:0xf bound_ctrl:1
	v_cndmask_b32_e64 v113, v167, v168, s[10:11]
	v_mov_b32_dpp v168, v204 row_ror:1 row_mask:0xf bank_mask:0xf bound_ctrl:1
	v_cndmask_b32_e64 v126, v171, v170, s[12:13]
	v_mov_b32_dpp v171, v205 row_ror:2 row_mask:0xf bank_mask:0xf bound_ctrl:1
	v_cndmask_b32_e64 v122, v217, v176, s[12:13]
	v_cndmask_b32_e64 v124, v168, v169, s[10:11]
	v_mov_b32_dpp v169, v205 row_ror:1 row_mask:0xf bank_mask:0xf bound_ctrl:1
	v_cndmask_b32_e64 v127, v174, v171, s[12:13]
	v_cndmask_b32_e64 v125, v169, v172, s[10:11]
	v_pk_fma_f32 v[122:123], v[154:155], v[122:123], v[158:159]
	v_pk_fma_f32 v[126:127], v[156:157], v[126:127], v[160:161]
	v_pk_fma_f32 v[112:113], v[150:151], v[112:113], v[122:123]
	v_pk_fma_f32 v[122:123], v[152:153], v[124:125], v[126:127]
	v_mul_f32_e32 v124, 0xbfb8aa3b, v108
	v_mul_f32_e32 v125, 0xbfb8aa3b, v109
	v_mul_f32_e32 v126, 0xbfb8aa3b, v110
	v_mul_f32_e32 v127, 0xbfb8aa3b, v111
	v_exp_f32_e32 v124, v124
	v_exp_f32_e32 v125, v125
	v_exp_f32_e32 v126, v126
	v_exp_f32_e32 v127, v127
	v_add_f32_e32 v124, 1.0, v124
	v_add_f32_e32 v125, 1.0, v125
	v_add_f32_e32 v126, 1.0, v126
	v_add_f32_e32 v127, 1.0, v127
	v_rcp_f32_e32 v124, v124
	v_rcp_f32_e32 v125, v125
	v_rcp_f32_e32 v126, v126
	v_rcp_f32_e32 v127, v127
	v_pk_fma_f32 v[112:113], v[206:207], v[146:147], v[112:113]
	v_pk_fma_f32 v[122:123], v[204:205], v[148:149], v[122:123]
	v_pk_mul_f32 v[108:109], v[108:109], v[124:125]
	v_pk_mul_f32 v[110:111], v[110:111], v[126:127]
	v_mov_b32_dpp v127, v106 row_ror:2 row_mask:0xf bank_mask:0xf bound_ctrl:1
	v_pk_mul_f32 v[108:109], v[108:109], v[112:113]
	v_pk_mul_f32 v[110:111], v[110:111], v[122:123]
	v_mov_b32_dpp v126, v106 row_ror:1 row_mask:0xf bank_mask:0xf bound_ctrl:1
	v_cndmask_b32_e64 v112, v129, v127, s[12:13]
	v_mov_b32_dpp v129, v107 row_ror:2 row_mask:0xf bank_mask:0xf bound_ctrl:1
	v_cvt_pk_bf16_f32 v108, v108, v109
	v_cvt_pk_bf16_f32 v109, v110, v111
	v_cndmask_b32_e64 v110, v126, v128, s[10:11]
	v_mov_b32_dpp v128, v107 row_ror:1 row_mask:0xf bank_mask:0xf bound_ctrl:1
	v_cndmask_b32_e64 v113, v163, v129, s[12:13]
	v_mov_b32_dpp v163, v104 row_ror:2 row_mask:0xf bank_mask:0xf bound_ctrl:1
	v_cndmask_b32_e64 v111, v128, v162, s[10:11]
	v_mov_b32_dpp v162, v104 row_ror:1 row_mask:0xf bank_mask:0xf bound_ctrl:1
	v_cndmask_b32_e64 v124, v165, v163, s[12:13]
	v_mov_b32_dpp v165, v105 row_ror:2 row_mask:0xf bank_mask:0xf bound_ctrl:1
	v_pk_fma_f32 v[112:113], v[138:139], v[112:113], v[142:143]
	v_cndmask_b32_e64 v122, v162, v164, s[10:11]
	v_mov_b32_dpp v164, v105 row_ror:1 row_mask:0xf bank_mask:0xf bound_ctrl:1
	v_cndmask_b32_e64 v125, v175, v165, s[12:13]
	v_pk_fma_f32 v[110:111], v[134:135], v[110:111], v[112:113]
	v_mov_b32_dpp v172, v98 row_ror:1 row_mask:0xf bank_mask:0xf bound_ctrl:1
	v_cndmask_b32_e64 v123, v164, v173, s[10:11]
	v_pk_fma_f32 v[124:125], v[140:141], v[124:125], v[144:145]
	v_pk_fma_f32 v[106:107], v[106:107], v[130:131], v[110:111]
	v_cndmask_b32_e64 v110, v172, v166, s[10:11]
	v_mov_b32_dpp v166, v99 row_ror:1 row_mask:0xf bank_mask:0xf bound_ctrl:1
	v_mov_b32_dpp v175, v102 row_ror:2 row_mask:0xf bank_mask:0xf bound_ctrl:1
	v_pk_fma_f32 v[112:113], v[136:137], v[122:123], v[124:125]
	v_mov_b32_dpp v173, v98 row_ror:2 row_mask:0xf bank_mask:0xf bound_ctrl:1
	v_mov_b32_dpp v174, v99 row_ror:2 row_mask:0xf bank_mask:0xf bound_ctrl:1
	v_cndmask_b32_e64 v111, v166, v167, s[10:11]
	v_mov_b32_dpp v167, v102 row_ror:1 row_mask:0xf bank_mask:0xf bound_ctrl:1
	v_cndmask_b32_e64 v124, v170, v175, s[12:13]
	v_mov_b32_dpp v170, v103 row_ror:2 row_mask:0xf bank_mask:0xf bound_ctrl:1
	v_pk_fma_f32 v[104:105], v[104:105], v[132:133], v[112:113]
	v_cndmask_b32_e64 v112, v176, v173, s[12:13]
	v_cndmask_b32_e64 v113, v177, v174, s[12:13]
	v_cndmask_b32_e64 v122, v167, v168, s[10:11]
	v_mov_b32_dpp v168, v103 row_ror:1 row_mask:0xf bank_mask:0xf bound_ctrl:1
	v_cndmask_b32_e64 v125, v171, v170, s[12:13]
	v_cndmask_b32_e64 v123, v168, v169, s[10:11]
	v_pk_fma_f32 v[124:125], v[156:157], v[124:125], v[160:161]
	v_pk_fma_f32 v[112:113], v[154:155], v[112:113], v[158:159]
	v_lshl_add_u64 v[196:197], v[194:195], 1, s[34:35]
	v_pk_fma_f32 v[110:111], v[150:151], v[110:111], v[112:113]
	v_pk_fma_f32 v[112:113], v[152:153], v[122:123], v[124:125]
	v_mul_f32_e32 v122, 0xbfb8aa3b, v106
	v_mul_f32_e32 v123, 0xbfb8aa3b, v107
; #define LAS __attribute__((address_space(3)))
; __device__ __forceinline__ float silu_f(float x) { return x * __builtin_amdgcn_rcpf(1.0f + __expf(-x)); }
;     __device__ __forceinline__ void operator()(const f32x4 (&acc_)[2][2][4][2], const pg8::Unit& u, int wr, int wc, int fr, int fq) const {
;     ...
;                 f32x4 w[2][3], bia[2], hm1[2], hm2[2];
; #pragma unroll
;                 for (int bj = 0; bj < 2; ++bj) {
;                     const int cc = bj * DFF + ch + 4 * eh;
; #pragma unroll
;                     for (int j = 0; j < 3; ++j) w[bj][j] = *(const LAS f32x4*)(cwl + (2 * j + bj) * 128 + 4 * eh);
;                     bia[bj] = *(const LAS f32x4*)(cwl + (6 + bj) * 128 + 4 * eh);
;                     if (!prompt) { const float* ps = past + (size_t)((blk0 - MP) >> 6) * 2 * DFF2 + cc; hm2[bj] = *(const f32x4*)ps; hm1[bj] = *(const f32x4*)(ps + DFF2); }
;                     else if (ai == 0 && wr == 0) { hm1[bj] = (f32x4){0.f, 0.f, 0.f, 0.f}; hm2[bj] = hm1[bj]; }
;                     else { const int pb = ai * 2 + wr - 1; const LAS float* s = hl + (((pb * 4 + wc) * 2 + 0) * 4 + fq) * 16 + bj * 8 + 4 * eh; hm2[bj] = *(const LAS f32x4*)s; hm1[bj] = *(const LAS f32x4*)(s + 64); }
;     ...
;                 for (int m = 0; m < 4; ++m) {
;                     f32x4 c[2];
; #pragma unroll
;                     for (int bj = 0; bj < 2; ++bj) {
;                         const f32x4 h0 = acc[ai][bj][m][eh]; f32x4 p1, p2;
; #pragma unroll
;                         for (int e = 0; e < 4; ++e) {
;                             const float r1 = dpp_ror1(h0[e]), r2 = dpp_ror2(h0[e]);
;                             p1[e] = (fr >= 1) ? r1 : pr1[bj][e]; p2[e] = (fr >= 2) ? r2 : pr2[bj][e];
;                             pr1[bj][e] = r1; pr2[bj][e] = r2;
;                         }
;                         c[bj] = bia[bj] + w[bj][0] * p2 + w[bj][1] * p1 + w[bj][2] * h0;
;                     }
;                     f32x4 o;
; #pragma unroll
;                     for (int e = 0; e < 4; ++e) o[e] = silu_f(c[0][e]) * c[1][e];
;                     pk[m].x = cvt_pk_bf16(o[0], o[1]); pk[m].y = cvt_pk_bf16(o[2], o[3]);
;                 }
; #pragma unroll
;                 for (int m = 0; m < 4; ++m) *(u32x2*)(act + (size_t)(blk0 + 16 * m + fr) * DFF + ch + 4 * eh) = pk[m];
	v_exp_f32_e32 v122, v122
	v_exp_f32_e32 v123, v123
	v_pk_fma_f32 v[102:103], v[102:103], v[148:149], v[112:113]
	v_pk_fma_f32 v[98:99], v[98:99], v[146:147], v[110:111]
	v_add_f32_e32 v112, 1.0, v122
	v_add_f32_e32 v113, 1.0, v123
	v_mul_f32_e32 v122, 0xbfb8aa3b, v104
	v_mul_f32_e32 v123, 0xbfb8aa3b, v105
	v_exp_f32_e32 v122, v122
	v_exp_f32_e32 v123, v123
	v_rcp_f32_e32 v112, v112
	v_rcp_f32_e32 v113, v113
	v_add_f32_e32 v122, 1.0, v122
	v_add_f32_e32 v123, 1.0, v123
	v_rcp_f32_e32 v122, v122
	v_rcp_f32_e32 v123, v123
	v_pk_mul_f32 v[106:107], v[106:107], v[112:113]
	v_mov_b32_dpp v111, v121 row_ror:2 row_mask:0xf bank_mask:0xf bound_ctrl:1
	v_pk_mul_f32 v[98:99], v[106:107], v[98:99]
	v_pk_mul_f32 v[104:105], v[104:105], v[122:123]
	v_cvt_pk_bf16_f32 v98, v98, v99
	v_pk_mul_f32 v[102:103], v[104:105], v[102:103]
	v_mov_b32_dpp v105, v119 row_ror:2 row_mask:0xf bank_mask:0xf bound_ctrl:1
	v_cvt_pk_bf16_f32 v99, v102, v103
	v_mov_b32_dpp v103, v118 row_ror:2 row_mask:0xf bank_mask:0xf bound_ctrl:1
	v_mov_b32_dpp v107, v120 row_ror:2 row_mask:0xf bank_mask:0xf bound_ctrl:1
	v_mov_b32_dpp v102, v118 row_ror:1 row_mask:0xf bank_mask:0xf bound_ctrl:1
	v_cndmask_b32_e64 v104, v127, v103, s[12:13]
	v_mov_b32_dpp v103, v119 row_ror:1 row_mask:0xf bank_mask:0xf bound_ctrl:1
	v_cndmask_b32_e64 v105, v129, v105, s[12:13]
	v_mov_b32_dpp v106, v120 row_ror:1 row_mask:0xf bank_mask:0xf bound_ctrl:1
	v_cndmask_b32_e64 v110, v163, v107, s[12:13]
	v_mov_b32_dpp v107, v121 row_ror:1 row_mask:0xf bank_mask:0xf bound_ctrl:1
	v_cndmask_b32_e64 v111, v165, v111, s[12:13]
	v_cndmask_b32_e64 v102, v102, v126, s[10:11]
	v_cndmask_b32_e64 v103, v103, v128, s[10:11]
	v_cndmask_b32_e64 v106, v106, v162, s[10:11]
	v_cndmask_b32_e64 v107, v107, v164, s[10:11]
	v_pk_fma_f32 v[104:105], v[138:139], v[104:105], v[142:143]
	v_pk_fma_f32 v[110:111], v[140:141], v[110:111], v[144:145]
	v_pk_fma_f32 v[102:103], v[134:135], v[102:103], v[104:105]
	v_pk_fma_f32 v[104:105], v[136:137], v[106:107], v[110:111]
	v_mov_b32_dpp v107, v114 row_ror:2 row_mask:0xf bank_mask:0xf bound_ctrl:1
	v_mov_b32_dpp v111, v115 row_ror:2 row_mask:0xf bank_mask:0xf bound_ctrl:1
	v_pk_fma_f32 v[102:103], v[118:119], v[130:131], v[102:103]
	v_mov_b32_dpp v106, v114 row_ror:1 row_mask:0xf bank_mask:0xf bound_ctrl:1
	v_cndmask_b32_e64 v110, v173, v107, s[12:13]
	v_mov_b32_dpp v107, v115 row_ror:1 row_mask:0xf bank_mask:0xf bound_ctrl:1
	v_cndmask_b32_e64 v111, v174, v111, s[12:13]
	v_mov_b32_dpp v113, v116 row_ror:2 row_mask:0xf bank_mask:0xf bound_ctrl:1
	v_mov_b32_dpp v119, v117 row_ror:2 row_mask:0xf bank_mask:0xf bound_ctrl:1
	v_cndmask_b32_e64 v106, v106, v172, s[10:11]
	v_cndmask_b32_e64 v107, v107, v166, s[10:11]
	v_mov_b32_dpp v112, v116 row_ror:1 row_mask:0xf bank_mask:0xf bound_ctrl:1
	v_cndmask_b32_e64 v118, v175, v113, s[12:13]
	v_mov_b32_dpp v113, v117 row_ror:1 row_mask:0xf bank_mask:0xf bound_ctrl:1
	v_cndmask_b32_e64 v119, v170, v119, s[12:13]
	v_pk_fma_f32 v[110:111], v[154:155], v[110:111], v[158:159]
	v_pk_fma_f32 v[104:105], v[120:121], v[132:133], v[104:105]
	v_cndmask_b32_e64 v112, v112, v167, s[10:11]
	v_cndmask_b32_e64 v113, v113, v168, s[10:11]
	v_pk_fma_f32 v[118:119], v[156:157], v[118:119], v[160:161]
	v_pk_fma_f32 v[106:107], v[150:151], v[106:107], v[110:111]
	v_pk_fma_f32 v[110:111], v[152:153], v[112:113], v[118:119]
	v_mul_f32_e32 v112, 0xbfb8aa3b, v102
	v_mul_f32_e32 v113, 0xbfb8aa3b, v103
	v_pk_fma_f32 v[106:107], v[114:115], v[146:147], v[106:107]
	v_mul_f32_e32 v114, 0xbfb8aa3b, v104
	v_mul_f32_e32 v115, 0xbfb8aa3b, v105
	v_exp_f32_e32 v112, v112
	v_exp_f32_e32 v113, v113
	v_exp_f32_e32 v114, v114
	v_exp_f32_e32 v115, v115
	v_add_f32_e32 v112, 1.0, v112
	v_add_f32_e32 v113, 1.0, v113
	v_add_f32_e32 v114, 1.0, v114
	v_add_f32_e32 v115, 1.0, v115
	v_rcp_f32_e32 v112, v112
	v_rcp_f32_e32 v113, v113
	v_rcp_f32_e32 v114, v114
	v_rcp_f32_e32 v115, v115
	v_pk_fma_f32 v[110:111], v[116:117], v[148:149], v[110:111]
	v_pk_mul_f32 v[102:103], v[102:103], v[112:113]
	v_or_b32_e32 v211, s37, v210
	v_pk_mul_f32 v[104:105], v[104:105], v[114:115]
	v_pk_mul_f32 v[102:103], v[102:103], v[106:107]
	v_pk_mul_f32 v[104:105], v[104:105], v[110:111]
	s_movk_i32 s22, 0x2c00
	v_cvt_pk_bf16_f32 v114, v102, v103
	v_cvt_pk_bf16_f32 v115, v104, v105
	v_mad_i64_i32 v[148:149], s[2:3], v211, s22, v[196:197]
	global_store_dwordx2 v[148:149], v[100:101], off
	v_or_b32_e32 v100, 16, v211
	v_mad_i64_i32 v[150:151], s[2:3], v100, s22, v[196:197]
	v_or_b32_e32 v100, 32, v211
	v_mad_i64_i32 v[152:153], s[2:3], v100, s22, v[196:197]
	global_store_dwordx2 v[150:151], v[108:109], off
	global_store_dwordx2 v[152:153], v[98:99], off
	ds_read_b128 v[106:109], v0 offset:16
	ds_read_b128 v[102:105], v0 offset:1040
	ds_read_b128 v[98:101], v0 offset:2064
	ds_read_b128 v[110:113], v0 offset:3088
	v_or_b32_e32 v116, 48, v211
	v_mad_i64_i32 v[154:155], s[2:3], v116, s22, v[196:197]
	s_and_b64 vcc, exec, s[8:9]
	s_mov_b64 s[2:3], -1
	global_store_dwordx2 v[154:155], v[114:115], off
	s_cbranch_vccnz .LBB0_1830
	v_add_co_u32_e32 v114, vcc, 0xb000, v202
	s_mov_b64 s[2:3], 0
	s_nop 0
	v_addc_co_u32_e32 v115, vcc, 0, v203, vcc
	global_load_dwordx4 v[134:137], v[202:203], off offset:16
	global_load_dwordx4 v[130:133], v[114:115], off offset:16
.LBB0_1830:
	s_andn2_b64 vcc, exec, s[2:3]
	s_cbranch_vccnz .LBB0_1835
	s_and_b64 vcc, exec, s[14:15]
	s_mov_b64 s[2:3], -1
	s_cbranch_vccnz .LBB0_1833
	v_add_u32_e32 v114, 0xfffff810, v191
	v_add_u32_e32 v115, 0xfffff910, v191
	ds_read_b128 v[134:137], v114
	ds_read_b128 v[130:133], v115
	s_mov_b64 s[2:3], 0
.LBB0_1833:
	s_andn2_b64 vcc, exec, s[2:3]
	s_cbranch_vccnz .LBB0_1835
	s_waitcnt lgkmcnt(0)
	v_mov_b32_e32 v133, 0
	v_mov_b32_e32 v132, v133
	v_mov_b32_e32 v131, v133
	v_mov_b32_e32 v130, v133
	v_mov_b32_e32 v137, v133
	v_mov_b32_e32 v136, v133
	v_mov_b32_e32 v135, v133
	v_mov_b32_e32 v134, v133

; #define LAS __attribute__((address_space(3)))
; __device__ __forceinline__ unsigned cvt_pk_bf16(float lo, float hi) { const f32x2 v = {lo, hi}; unsigned r = __builtin_bit_cast(unsigned, __builtin_convertvector(v, bf16x2_t)); asm volatile("" : "+v"(r)); return r; }
; __device__ __forceinline__ float silu_f(float x) { return x * __builtin_amdgcn_rcpf(1.0f + __expf(-x)); }
;     __device__ __forceinline__ void operator()(const f32x4 (&acc_)[2][2][4][2], const pg8::Unit& u, int wr, int wc, int fr, int fq) const {
;     ...
;                     if (!prompt) { const float* ps = past + (size_t)((blk0 - MP) >> 6) * 2 * DFF2 + cc; hm2[bj] = *(const f32x4*)ps; hm1[bj] = *(const f32x4*)(ps + DFF2); }
;                     else if (ai == 0 && wr == 0) { hm1[bj] = (f32x4){0.f, 0.f, 0.f, 0.f}; hm2[bj] = hm1[bj]; }
;                     else { const int pb = ai * 2 + wr - 1; const LAS float* s = hl + (((pb * 4 + wc) * 2 + 0) * 4 + fq) * 16 + bj * 8 + 4 * eh; hm2[bj] = *(const LAS f32x4*)s; hm1[bj] = *(const LAS f32x4*)(s + 64); }
;                 }
;                 u32x2 pk[4]; f32x4 pr1[2], pr2[2];
; #pragma unroll
;                 for (int bj = 0; bj < 2; ++bj)
; #pragma unroll
;                     for (int e = 0; e < 4; ++e) { pr1[bj][e] = hm1[bj][e]; pr2[bj][e] = (fr == 0) ? hm2[bj][e] : hm1[bj][e]; }
; #pragma unroll
;                 for (int m = 0; m < 4; ++m) {
;                     f32x4 c[2];
; #pragma unroll
;                     for (int bj = 0; bj < 2; ++bj) {
;                         const f32x4 h0 = acc[ai][bj][m][eh]; f32x4 p1, p2;
; #pragma unroll
;                         for (int e = 0; e < 4; ++e) {
;                             const float r1 = dpp_ror1(h0[e]), r2 = dpp_ror2(h0[e]);
;                             p1[e] = (fr >= 1) ? r1 : pr1[bj][e]; p2[e] = (fr >= 2) ? r2 : pr2[bj][e];
;                             pr1[bj][e] = r1; pr2[bj][e] = r2;
;                         }
;                         c[bj] = bia[bj] + w[bj][0] * p2 + w[bj][1] * p1 + w[bj][2] * h0;
;                     }
;                     f32x4 o;
; #pragma unroll
;                     for (int e = 0; e < 4; ++e) o[e] = silu_f(c[0][e]) * c[1][e];
;                     pk[m].x = cvt_pk_bf16(o[0], o[1]); pk[m].y = cvt_pk_bf16(o[2], o[3]);
;                 }
.LBB0_1837:
	s_andn2_b64 vcc, exec, s[2:3]
	v_readlane_b32 s46, v255, 29
	s_cbranch_vccnz .LBB0_1842
	s_and_b64 vcc, exec, s[14:15]
	s_mov_b64 s[2:3], -1
	s_cbranch_vccnz .LBB0_1840
	v_add_u32_e32 v138, 0xfffff830, v191
	v_add_u32_e32 v139, 0xfffff930, v191
	ds_read_b128 v[142:145], v138
	ds_read_b128 v[138:141], v139
	s_mov_b64 s[2:3], 0
.LBB0_1840:
	s_andn2_b64 vcc, exec, s[2:3]
	s_cbranch_vccnz .LBB0_1842
	s_waitcnt lgkmcnt(0)
	v_mov_b32_e32 v141, 0
	v_mov_b32_e32 v140, v141
	v_mov_b32_e32 v139, v141
	v_mov_b32_e32 v138, v141
	v_mov_b32_e32 v145, v141
	v_mov_b32_e32 v144, v141
	v_mov_b32_e32 v143, v141
	v_mov_b32_e32 v142, v141
.LBB0_1842:
	v_mov_b32_e32 v156, v198
	v_mov_b32_e32 v157, v198
	v_mov_b32_e32 v160, v198
	v_mov_b32_e32 v161, v198
	v_mov_b32_e32 v198, v199
	v_mov_b32_e32 v158, v199
	v_mov_b32_e32 v159, v199
	v_pk_mul_f32 v[70:71], v[70:71], v[156:157]
	v_pk_mul_f32 v[156:157], v[62:63], v[156:157]
	v_pk_mul_f32 v[62:63], v[60:61], v[198:199]
	s_waitcnt lgkmcnt(4)
	s_and_b64 vcc, exec, s[8:9]
	s_cbranch_vccnz .Leu_j1842
	s_waitcnt vmcnt(0)
.Leu_j1842:
	v_cndmask_b32_e64 v61, v130, v134, s[10:11]
	v_cndmask_b32_e64 v134, v132, v136, s[10:11]
	s_waitcnt lgkmcnt(0)
	v_cndmask_b32_e64 v136, v138, v142, s[10:11]
	v_cndmask_b32_e64 v142, v140, v144, s[10:11]
	v_mov_b32_dpp v144, v94 row_ror:1 row_mask:0xf bank_mask:0xf bound_ctrl:1
	v_mov_b32_dpp v162, v96 row_ror:1 row_mask:0xf bank_mask:0xf bound_ctrl:1
	v_mov_b32_dpp v163, v96 row_ror:2 row_mask:0xf bank_mask:0xf bound_ctrl:1
	v_pk_mul_f32 v[72:73], v[72:73], v[160:161]
	v_pk_mul_f32 v[160:161], v[64:65], v[160:161]
	v_pk_mul_f32 v[64:65], v[68:69], v[198:199]
	v_pk_mul_f32 v[66:67], v[66:67], v[158:159]
	v_pk_mul_f32 v[58:59], v[58:59], v[158:159]
	v_cndmask_b32_e64 v69, v131, v135, s[10:11]
	v_cndmask_b32_e64 v135, v133, v137, s[10:11]
	v_cndmask_b32_e64 v137, v139, v143, s[10:11]
	v_cndmask_b32_e64 v143, v141, v145, s[10:11]
	v_mov_b32_dpp v145, v94 row_ror:2 row_mask:0xf bank_mask:0xf bound_ctrl:1
	v_cndmask_b32_e64 v60, v144, v130, s[10:11]
	v_mov_b32_dpp v158, v95 row_ror:1 row_mask:0xf bank_mask:0xf bound_ctrl:1
	v_mov_b32_dpp v159, v95 row_ror:2 row_mask:0xf bank_mask:0xf bound_ctrl:1
	v_cndmask_b32_e64 v130, v162, v132, s[10:11]
	v_cndmask_b32_e64 v132, v134, v163, s[12:13]
	v_mov_b32_dpp v134, v97 row_ror:1 row_mask:0xf bank_mask:0xf bound_ctrl:1
	v_mov_b32_dpp v164, v97 row_ror:2 row_mask:0xf bank_mask:0xf bound_ctrl:1
	v_cndmask_b32_e64 v68, v61, v145, s[12:13]
	v_cndmask_b32_e64 v61, v158, v131, s[10:11]
	v_cndmask_b32_e64 v69, v69, v159, s[12:13]
	v_cndmask_b32_e64 v131, v134, v133, s[10:11]
	v_cndmask_b32_e64 v133, v135, v164, s[12:13]
	v_pk_fma_f32 v[132:133], v[108:109], v[132:133], v[112:113]
	v_pk_fma_f32 v[68:69], v[106:107], v[68:69], v[110:111]
	v_mov_b32_dpp v165, v90 row_ror:2 row_mask:0xf bank_mask:0xf bound_ctrl:1
	v_pk_fma_f32 v[60:61], v[102:103], v[60:61], v[68:69]
	v_pk_fma_f32 v[68:69], v[104:105], v[130:131], v[132:133]
	v_mov_b32_dpp v135, v90 row_ror:1 row_mask:0xf bank_mask:0xf bound_ctrl:1
	v_pk_fma_f32 v[68:69], v[96:97], v[100:101], v[68:69]
	v_cndmask_b32_e64 v96, v136, v165, s[12:13]
	v_mov_b32_dpp v136, v91 row_ror:1 row_mask:0xf bank_mask:0xf bound_ctrl:1
	v_pk_fma_f32 v[60:61], v[94:95], v[98:99], v[60:61]
	v_cndmask_b32_e64 v94, v135, v138, s[10:11]
	v_mov_b32_dpp v138, v91 row_ror:2 row_mask:0xf bank_mask:0xf bound_ctrl:1
	v_cndmask_b32_e64 v95, v136, v139, s[10:11]
	v_mov_b32_dpp v139, v92 row_ror:2 row_mask:0xf bank_mask:0xf bound_ctrl:1
	v_cndmask_b32_e64 v97, v137, v138, s[12:13]
	v_mov_b32_dpp v137, v92 row_ror:1 row_mask:0xf bank_mask:0xf bound_ctrl:1
	v_cndmask_b32_e64 v132, v142, v139, s[12:13]
	v_mov_b32_dpp v142, v93 row_ror:2 row_mask:0xf bank_mask:0xf bound_ctrl:1
	v_cndmask_b32_e64 v130, v137, v140, s[10:11]
	v_mov_b32_dpp v140, v93 row_ror:1 row_mask:0xf bank_mask:0xf bound_ctrl:1
	v_cndmask_b32_e64 v133, v143, v142, s[12:13]
	v_cndmask_b32_e64 v131, v140, v141, s[10:11]
	v_pk_fma_f32 v[132:133], v[124:125], v[132:133], v[128:129]
	v_pk_fma_f32 v[96:97], v[122:123], v[96:97], v[126:127]
	v_mov_b32_dpp v143, v73 row_ror:2 row_mask:0xf bank_mask:0xf bound_ctrl:1
	v_pk_fma_f32 v[94:95], v[118:119], v[94:95], v[96:97]
	v_pk_fma_f32 v[96:97], v[120:121], v[130:131], v[132:133]
	v_mul_f32_e32 v130, 0xbfb8aa3b, v60
	v_mul_f32_e32 v131, 0xbfb8aa3b, v61
	v_exp_f32_e32 v130, v130
	v_exp_f32_e32 v131, v131
	v_pk_fma_f32 v[92:93], v[92:93], v[116:117], v[96:97]
	v_pk_fma_f32 v[90:91], v[90:91], v[114:115], v[94:95]
	v_add_f32_e32 v96, 1.0, v130
	v_add_f32_e32 v97, 1.0, v131
	v_mul_f32_e32 v130, 0xbfb8aa3b, v68
	v_mul_f32_e32 v131, 0xbfb8aa3b, v69
	v_exp_f32_e32 v130, v130
	v_exp_f32_e32 v131, v131
	v_rcp_f32_e32 v96, v96
	v_rcp_f32_e32 v97, v97
	v_add_f32_e32 v130, 1.0, v130
	v_add_f32_e32 v131, 1.0, v131
	v_rcp_f32_e32 v130, v130
	v_rcp_f32_e32 v131, v131
	v_pk_mul_f32 v[60:61], v[60:61], v[96:97]
	v_mov_b32_dpp v97, v70 row_ror:2 row_mask:0xf bank_mask:0xf bound_ctrl:1
	v_mov_b32_dpp v133, v72 row_ror:2 row_mask:0xf bank_mask:0xf bound_ctrl:1
	v_pk_mul_f32 v[68:69], v[68:69], v[130:131]
	v_mov_b32_dpp v131, v71 row_ror:2 row_mask:0xf bank_mask:0xf bound_ctrl:1
	v_pk_mul_f32 v[60:61], v[60:61], v[90:91]
	v_pk_mul_f32 v[68:69], v[68:69], v[92:93]
	v_mov_b32_dpp v96, v70 row_ror:1 row_mask:0xf bank_mask:0xf bound_ctrl:1
	v_cndmask_b32_e64 v90, v145, v97, s[12:13]
	v_mov_b32_dpp v130, v71 row_ror:1 row_mask:0xf bank_mask:0xf bound_ctrl:1
	v_cndmask_b32_e64 v91, v159, v131, s[12:13]
	v_mov_b32_dpp v132, v72 row_ror:1 row_mask:0xf bank_mask:0xf bound_ctrl:1
	v_cndmask_b32_e64 v94, v163, v133, s[12:13]
; __device__ __forceinline__ unsigned cvt_pk_bf16(float lo, float hi) { const f32x2 v = {lo, hi}; unsigned r = __builtin_bit_cast(unsigned, __builtin_convertvector(v, bf16x2_t)); asm volatile("" : "+v"(r)); return r; }
; __device__ __forceinline__ float silu_f(float x) { return x * __builtin_amdgcn_rcpf(1.0f + __expf(-x)); }
; __device__ __forceinline__ float dpp_ror1(float x) { return __builtin_bit_cast(float, __builtin_amdgcn_update_dpp(0, __builtin_bit_cast(int, x), 0x121, 0xf, 0xf, true)); }
; __device__ __forceinline__ float dpp_ror2(float x) { return __builtin_bit_cast(float, __builtin_amdgcn_update_dpp(0, __builtin_bit_cast(int, x), 0x122, 0xf, 0xf, true)); }
;     __device__ __forceinline__ void operator()(const f32x4 (&acc_)[2][2][4][2], const pg8::Unit& u, int wr, int wc, int fr, int fq) const {
;     ...
;                 for (int m = 0; m < 4; ++m) {
;                     f32x4 c[2];
; #pragma unroll
;                     for (int bj = 0; bj < 2; ++bj) {
;                         const f32x4 h0 = acc[ai][bj][m][eh]; f32x4 p1, p2;
; #pragma unroll
;                         for (int e = 0; e < 4; ++e) {
;                             const float r1 = dpp_ror1(h0[e]), r2 = dpp_ror2(h0[e]);
;                             p1[e] = (fr >= 1) ? r1 : pr1[bj][e]; p2[e] = (fr >= 2) ? r2 : pr2[bj][e];
;                             pr1[bj][e] = r1; pr2[bj][e] = r2;
;                         }
;                         c[bj] = bia[bj] + w[bj][0] * p2 + w[bj][1] * p1 + w[bj][2] * h0;
;                     }
;                     f32x4 o;
; #pragma unroll
;                     for (int e = 0; e < 4; ++e) o[e] = silu_f(c[0][e]) * c[1][e];
;                     pk[m].x = cvt_pk_bf16(o[0], o[1]); pk[m].y = cvt_pk_bf16(o[2], o[3]);
;                 }
	v_mov_b32_dpp v141, v73 row_ror:1 row_mask:0xf bank_mask:0xf bound_ctrl:1
	v_cndmask_b32_e64 v95, v164, v143, s[12:13]
	v_cvt_pk_bf16_f32 v60, v60, v61
	v_cvt_pk_bf16_f32 v61, v68, v69
	v_cndmask_b32_e64 v68, v96, v144, s[10:11]
	v_cndmask_b32_e64 v69, v130, v158, s[10:11]
	v_cndmask_b32_e64 v92, v132, v162, s[10:11]
	v_cndmask_b32_e64 v93, v141, v134, s[10:11]
	v_pk_fma_f32 v[94:95], v[108:109], v[94:95], v[112:113]
	v_pk_fma_f32 v[90:91], v[106:107], v[90:91], v[110:111]
	v_mov_b32_dpp v134, v156 row_ror:1 row_mask:0xf bank_mask:0xf bound_ctrl:1
	v_pk_fma_f32 v[68:69], v[102:103], v[68:69], v[90:91]
	v_pk_fma_f32 v[90:91], v[104:105], v[92:93], v[94:95]
	v_mov_b32_dpp v145, v157 row_ror:2 row_mask:0xf bank_mask:0xf bound_ctrl:1
	v_pk_fma_f32 v[72:73], v[72:73], v[100:101], v[90:91]
	v_pk_fma_f32 v[68:69], v[70:71], v[98:99], v[68:69]
	v_cndmask_b32_e64 v70, v134, v135, s[10:11]
	v_mov_b32_dpp v135, v157 row_ror:1 row_mask:0xf bank_mask:0xf bound_ctrl:1
	v_cndmask_b32_e64 v91, v138, v145, s[12:13]
	v_mov_b32_dpp v138, v160 row_ror:2 row_mask:0xf bank_mask:0xf bound_ctrl:1
	v_mov_b32_dpp v144, v156 row_ror:2 row_mask:0xf bank_mask:0xf bound_ctrl:1
	v_cndmask_b32_e64 v71, v135, v136, s[10:11]
	v_mov_b32_dpp v136, v160 row_ror:1 row_mask:0xf bank_mask:0xf bound_ctrl:1
	v_cndmask_b32_e64 v94, v139, v138, s[12:13]
	v_mov_b32_dpp v139, v161 row_ror:2 row_mask:0xf bank_mask:0xf bound_ctrl:1
	v_cndmask_b32_e64 v90, v165, v144, s[12:13]
	v_cndmask_b32_e64 v92, v136, v137, s[10:11]
	v_mov_b32_dpp v137, v161 row_ror:1 row_mask:0xf bank_mask:0xf bound_ctrl:1
	v_cndmask_b32_e64 v95, v142, v139, s[12:13]
	v_cndmask_b32_e64 v93, v137, v140, s[10:11]
	v_pk_fma_f32 v[94:95], v[124:125], v[94:95], v[128:129]
	v_pk_fma_f32 v[90:91], v[122:123], v[90:91], v[126:127]
	v_mov_b32_dpp v140, v58 row_ror:1 row_mask:0xf bank_mask:0xf bound_ctrl:1
	v_pk_fma_f32 v[70:71], v[118:119], v[70:71], v[90:91]
	v_pk_fma_f32 v[90:91], v[120:121], v[92:93], v[94:95]
	v_mul_f32_e32 v92, 0xbfb8aa3b, v68
	v_mul_f32_e32 v93, 0xbfb8aa3b, v69
	v_exp_f32_e32 v92, v92
	v_exp_f32_e32 v93, v93
	v_mul_f32_e32 v94, 0xbfb8aa3b, v72
	v_mul_f32_e32 v95, 0xbfb8aa3b, v73
	v_exp_f32_e32 v94, v94
	v_exp_f32_e32 v95, v95
	v_add_f32_e32 v92, 1.0, v92
	v_add_f32_e32 v93, 1.0, v93
	v_rcp_f32_e32 v92, v92
	v_rcp_f32_e32 v93, v93
	v_add_f32_e32 v94, 1.0, v94
	v_add_f32_e32 v95, 1.0, v95
	v_rcp_f32_e32 v94, v94
	v_rcp_f32_e32 v95, v95
	v_pk_fma_f32 v[70:71], v[156:157], v[114:115], v[70:71]
	v_pk_mul_f32 v[68:69], v[68:69], v[92:93]
	v_pk_fma_f32 v[90:91], v[160:161], v[116:117], v[90:91]
	v_pk_mul_f32 v[68:69], v[68:69], v[70:71]
	v_pk_mul_f32 v[70:71], v[72:73], v[94:95]
	v_mov_b32_dpp v95, v66 row_ror:2 row_mask:0xf bank_mask:0xf bound_ctrl:1
	v_pk_mul_f32 v[70:71], v[70:71], v[90:91]
	v_mov_b32_dpp v94, v66 row_ror:1 row_mask:0xf bank_mask:0xf bound_ctrl:1
	v_cndmask_b32_e64 v72, v97, v95, s[12:13]
	v_mov_b32_dpp v97, v67 row_ror:2 row_mask:0xf bank_mask:0xf bound_ctrl:1
	v_cvt_pk_bf16_f32 v68, v68, v69
	v_cvt_pk_bf16_f32 v69, v70, v71
	v_cndmask_b32_e64 v70, v94, v96, s[10:11]
	v_mov_b32_dpp v96, v67 row_ror:1 row_mask:0xf bank_mask:0xf bound_ctrl:1
	v_cndmask_b32_e64 v73, v131, v97, s[12:13]
	v_mov_b32_dpp v131, v64 row_ror:2 row_mask:0xf bank_mask:0xf bound_ctrl:1
	v_cndmask_b32_e64 v71, v96, v130, s[10:11]
	v_mov_b32_dpp v130, v64 row_ror:1 row_mask:0xf bank_mask:0xf bound_ctrl:1
	v_cndmask_b32_e64 v92, v133, v131, s[12:13]
	v_mov_b32_dpp v133, v65 row_ror:2 row_mask:0xf bank_mask:0xf bound_ctrl:1
	v_pk_fma_f32 v[72:73], v[106:107], v[72:73], v[110:111]
	v_cndmask_b32_e64 v90, v130, v132, s[10:11]
	v_mov_b32_dpp v132, v65 row_ror:1 row_mask:0xf bank_mask:0xf bound_ctrl:1
	v_cndmask_b32_e64 v93, v143, v133, s[12:13]
	v_pk_fma_f32 v[70:71], v[102:103], v[70:71], v[72:73]
	v_cndmask_b32_e64 v91, v132, v141, s[10:11]
	v_pk_fma_f32 v[92:93], v[108:109], v[92:93], v[112:113]
	v_pk_fma_f32 v[66:67], v[66:67], v[98:99], v[70:71]
	v_cndmask_b32_e64 v70, v140, v134, s[10:11]
	v_mov_b32_dpp v134, v59 row_ror:1 row_mask:0xf bank_mask:0xf bound_ctrl:1
	v_mov_b32_dpp v143, v62 row_ror:2 row_mask:0xf bank_mask:0xf bound_ctrl:1
	v_pk_fma_f32 v[90:91], v[104:105], v[90:91], v[92:93]
	v_cndmask_b32_e64 v71, v134, v135, s[10:11]
	v_mov_b32_dpp v135, v62 row_ror:1 row_mask:0xf bank_mask:0xf bound_ctrl:1
	v_cndmask_b32_e64 v92, v138, v143, s[12:13]
	v_mov_b32_dpp v138, v63 row_ror:2 row_mask:0xf bank_mask:0xf bound_ctrl:1
	v_pk_fma_f32 v[64:65], v[64:65], v[100:101], v[90:91]
	v_mov_b32_dpp v141, v58 row_ror:2 row_mask:0xf bank_mask:0xf bound_ctrl:1
	v_mov_b32_dpp v142, v59 row_ror:2 row_mask:0xf bank_mask:0xf bound_ctrl:1
	v_cndmask_b32_e64 v90, v135, v136, s[10:11]
	v_mov_b32_dpp v136, v63 row_ror:1 row_mask:0xf bank_mask:0xf bound_ctrl:1
	v_cndmask_b32_e64 v93, v139, v138, s[12:13]
	v_cndmask_b32_e64 v72, v144, v141, s[12:13]
	v_cndmask_b32_e64 v73, v145, v142, s[12:13]
	v_cndmask_b32_e64 v91, v136, v137, s[10:11]
	v_pk_fma_f32 v[92:93], v[124:125], v[92:93], v[128:129]
	v_pk_fma_f32 v[72:73], v[122:123], v[72:73], v[126:127]
	v_pk_fma_f32 v[90:91], v[120:121], v[90:91], v[92:93]
; #define LAS __attribute__((address_space(3)))
; __device__ __forceinline__ float silu_f(float x) { return x * __builtin_amdgcn_rcpf(1.0f + __expf(-x)); }
;     __device__ __forceinline__ void operator()(const f32x4 (&acc_)[2][2][4][2], const pg8::Unit& u, int wr, int wc, int fr, int fq) const {
;     ...
;                 f32x4 w[2][3], bia[2], hm1[2], hm2[2];
; #pragma unroll
;                 for (int bj = 0; bj < 2; ++bj) {
;                     const int cc = bj * DFF + ch + 4 * eh;
; #pragma unroll
;                     for (int j = 0; j < 3; ++j) w[bj][j] = *(const LAS f32x4*)(cwl + (2 * j + bj) * 128 + 4 * eh);
;                     bia[bj] = *(const LAS f32x4*)(cwl + (6 + bj) * 128 + 4 * eh);
;                     if (!prompt) { const float* ps = past + (size_t)((blk0 - MP) >> 6) * 2 * DFF2 + cc; hm2[bj] = *(const f32x4*)ps; hm1[bj] = *(const f32x4*)(ps + DFF2); }
;                     else if (ai == 0 && wr == 0) { hm1[bj] = (f32x4){0.f, 0.f, 0.f, 0.f}; hm2[bj] = hm1[bj]; }
;                     else { const int pb = ai * 2 + wr - 1; const LAS float* s = hl + (((pb * 4 + wc) * 2 + 0) * 4 + fq) * 16 + bj * 8 + 4 * eh; hm2[bj] = *(const LAS f32x4*)s; hm1[bj] = *(const LAS f32x4*)(s + 64); }
;     ...
;                 for (int m = 0; m < 4; ++m) {
;                     f32x4 c[2];
; #pragma unroll
;                     for (int bj = 0; bj < 2; ++bj) {
;                         const f32x4 h0 = acc[ai][bj][m][eh]; f32x4 p1, p2;
; #pragma unroll
;                         for (int e = 0; e < 4; ++e) {
;                             const float r1 = dpp_ror1(h0[e]), r2 = dpp_ror2(h0[e]);
;                             p1[e] = (fr >= 1) ? r1 : pr1[bj][e]; p2[e] = (fr >= 2) ? r2 : pr2[bj][e];
;                             pr1[bj][e] = r1; pr2[bj][e] = r2;
;                         }
;                         c[bj] = bia[bj] + w[bj][0] * p2 + w[bj][1] * p1 + w[bj][2] * h0;
;                     }
;                     f32x4 o;
; #pragma unroll
;                     for (int e = 0; e < 4; ++e) o[e] = silu_f(c[0][e]) * c[1][e];
;                     pk[m].x = cvt_pk_bf16(o[0], o[1]); pk[m].y = cvt_pk_bf16(o[2], o[3]);
;                 }
; #pragma unroll
;                 for (int m = 0; m < 4; ++m) *(u32x2*)(act + (size_t)(blk0 + 16 * m + fr) * DFF + ch + 4 * eh) = pk[m];
	v_pk_fma_f32 v[70:71], v[118:119], v[70:71], v[72:73]
	v_mul_f32_e32 v72, 0xbfb8aa3b, v66
	v_mul_f32_e32 v73, 0xbfb8aa3b, v67
	v_pk_fma_f32 v[62:63], v[62:63], v[116:117], v[90:91]
	v_mul_f32_e32 v90, 0xbfb8aa3b, v64
	v_mul_f32_e32 v91, 0xbfb8aa3b, v65
	v_exp_f32_e32 v72, v72
	v_exp_f32_e32 v73, v73
	v_exp_f32_e32 v90, v90
	v_exp_f32_e32 v91, v91
	v_add_f32_e32 v72, 1.0, v72
	v_add_f32_e32 v73, 1.0, v73
	v_add_f32_e32 v90, 1.0, v90
	v_add_f32_e32 v91, 1.0, v91
	v_rcp_f32_e32 v72, v72
	v_rcp_f32_e32 v73, v73
	v_rcp_f32_e32 v90, v90
	v_rcp_f32_e32 v91, v91
	v_pk_fma_f32 v[58:59], v[58:59], v[114:115], v[70:71]
	v_pk_mul_f32 v[66:67], v[66:67], v[72:73]
	v_mov_b32_dpp v71, v89 row_ror:2 row_mask:0xf bank_mask:0xf bound_ctrl:1
	v_pk_mul_f32 v[64:65], v[64:65], v[90:91]
	v_pk_mul_f32 v[58:59], v[66:67], v[58:59]
	v_pk_mul_f32 v[62:63], v[64:65], v[62:63]
	v_cvt_pk_bf16_f32 v58, v58, v59
	v_cvt_pk_bf16_f32 v59, v62, v63
	v_mov_b32_dpp v63, v86 row_ror:2 row_mask:0xf bank_mask:0xf bound_ctrl:1
	v_mov_b32_dpp v65, v87 row_ror:2 row_mask:0xf bank_mask:0xf bound_ctrl:1
	v_mov_b32_dpp v62, v86 row_ror:1 row_mask:0xf bank_mask:0xf bound_ctrl:1
	v_cndmask_b32_e64 v64, v95, v63, s[12:13]
	v_mov_b32_dpp v63, v87 row_ror:1 row_mask:0xf bank_mask:0xf bound_ctrl:1
	v_cndmask_b32_e64 v65, v97, v65, s[12:13]
	v_mov_b32_dpp v67, v88 row_ror:2 row_mask:0xf bank_mask:0xf bound_ctrl:1
	v_cndmask_b32_e64 v62, v62, v94, s[10:11]
	v_cndmask_b32_e64 v63, v63, v96, s[10:11]
	v_mov_b32_dpp v66, v88 row_ror:1 row_mask:0xf bank_mask:0xf bound_ctrl:1
	v_cndmask_b32_e64 v70, v131, v67, s[12:13]
	v_mov_b32_dpp v67, v89 row_ror:1 row_mask:0xf bank_mask:0xf bound_ctrl:1
	v_cndmask_b32_e64 v71, v133, v71, s[12:13]
	v_pk_fma_f32 v[64:65], v[106:107], v[64:65], v[110:111]
	v_cndmask_b32_e64 v66, v66, v130, s[10:11]
	v_cndmask_b32_e64 v67, v67, v132, s[10:11]
	v_pk_fma_f32 v[70:71], v[108:109], v[70:71], v[112:113]
	v_pk_fma_f32 v[62:63], v[102:103], v[62:63], v[64:65]
	v_pk_fma_f32 v[64:65], v[104:105], v[66:67], v[70:71]
	v_pk_fma_f32 v[62:63], v[86:87], v[98:99], v[62:63]
	v_mov_b32_dpp v67, v82 row_ror:2 row_mask:0xf bank_mask:0xf bound_ctrl:1
	v_mov_b32_dpp v71, v83 row_ror:2 row_mask:0xf bank_mask:0xf bound_ctrl:1
	v_mov_b32_dpp v73, v84 row_ror:2 row_mask:0xf bank_mask:0xf bound_ctrl:1
	v_mov_b32_dpp v87, v85 row_ror:2 row_mask:0xf bank_mask:0xf bound_ctrl:1
	v_mov_b32_dpp v66, v82 row_ror:1 row_mask:0xf bank_mask:0xf bound_ctrl:1
	v_cndmask_b32_e64 v70, v141, v67, s[12:13]
	v_mov_b32_dpp v67, v83 row_ror:1 row_mask:0xf bank_mask:0xf bound_ctrl:1
	v_cndmask_b32_e64 v71, v142, v71, s[12:13]
	v_mov_b32_dpp v72, v84 row_ror:1 row_mask:0xf bank_mask:0xf bound_ctrl:1
	v_cndmask_b32_e64 v86, v143, v73, s[12:13]
	v_mov_b32_dpp v73, v85 row_ror:1 row_mask:0xf bank_mask:0xf bound_ctrl:1
	v_cndmask_b32_e64 v87, v138, v87, s[12:13]
	v_cndmask_b32_e64 v66, v66, v140, s[10:11]
	v_cndmask_b32_e64 v67, v67, v134, s[10:11]
	v_cndmask_b32_e64 v72, v72, v135, s[10:11]
	v_cndmask_b32_e64 v73, v73, v136, s[10:11]
	v_pk_fma_f32 v[86:87], v[124:125], v[86:87], v[128:129]
	v_pk_fma_f32 v[70:71], v[122:123], v[70:71], v[126:127]
	v_pk_fma_f32 v[64:65], v[88:89], v[100:101], v[64:65]
	v_pk_fma_f32 v[66:67], v[118:119], v[66:67], v[70:71]
	v_pk_fma_f32 v[70:71], v[120:121], v[72:73], v[86:87]
	v_mul_f32_e32 v72, 0xbfb8aa3b, v62
	v_mul_f32_e32 v73, 0xbfb8aa3b, v63
	v_pk_fma_f32 v[70:71], v[84:85], v[116:117], v[70:71]
	v_mul_f32_e32 v84, 0xbfb8aa3b, v64
	v_mul_f32_e32 v85, 0xbfb8aa3b, v65
	v_exp_f32_e32 v72, v72
	v_exp_f32_e32 v73, v73
	v_exp_f32_e32 v84, v84
	v_exp_f32_e32 v85, v85
	v_add_f32_e32 v72, 1.0, v72
	v_add_f32_e32 v73, 1.0, v73
	v_add_f32_e32 v84, 1.0, v84
	v_add_f32_e32 v85, 1.0, v85
	v_rcp_f32_e32 v72, v72
	v_rcp_f32_e32 v73, v73
	v_rcp_f32_e32 v84, v84
	v_rcp_f32_e32 v85, v85
	v_pk_fma_f32 v[66:67], v[82:83], v[114:115], v[66:67]
	v_pk_mul_f32 v[62:63], v[62:63], v[72:73]
	v_pk_mul_f32 v[64:65], v[64:65], v[84:85]
	v_pk_mul_f32 v[62:63], v[62:63], v[66:67]
	v_pk_mul_f32 v[64:65], v[64:65], v[70:71]
	v_cvt_pk_bf16_f32 v62, v62, v63
	v_cvt_pk_bf16_f32 v63, v64, v65
	global_store_dwordx2 v[148:149], v[60:61], off offset:8
	global_store_dwordx2 v[150:151], v[68:69], off offset:8
	global_store_dwordx2 v[152:153], v[58:59], off offset:8
	global_store_dwordx2 v[154:155], v[62:63], off offset:8
	ds_read_b128 v[70:73], v0
	ds_read_b128 v[66:69], v0 offset:1024
	ds_read_b128 v[62:65], v0 offset:2048
	ds_read_b128 v[82:85], v0 offset:3072
	s_add_i32 s2, s37, 0xffffc080
	s_ashr_i32 s2, s2, 6
	s_mul_hi_i32 s3, s2, 0x16000
	s_mul_i32 s2, s2, 0x16000
	s_add_u32 s14, s81, s2
	s_addc_u32 s15, s92, s3
	s_mov_b64 s[2:3], -1
	s_and_b64 vcc, exec, s[8:9]
	v_lshl_add_u64 v[114:115], v[194:195], 2, s[14:15]
	s_cbranch_vccnz .LBB0_1844
	v_add_co_u32_e32 v58, vcc, 0xb000, v114
	s_mov_b64 s[2:3], 0
	s_nop 0
	v_addc_co_u32_e32 v59, vcc, 0, v115, vcc
	global_load_dwordx4 v[106:109], v[114:115], off
	global_load_dwordx4 v[98:101], v[58:59], off
.LBB0_1844:
	s_andn2_b64 vcc, exec, s[2:3]
	s_cbranch_vccnz .LBB0_1846
	ds_read_b128 v[106:109], v191 offset:2048
	ds_read_b128 v[98:101], v191 offset:2304

; #define LAS __attribute__((address_space(3)))
;     __device__ __forceinline__ void operator()(const f32x4 (&acc_)[2][2][4][2], const pg8::Unit& u, int wr, int wc, int fr, int fq) const {
;     ...
;                 f32x4 w[2][3], bia[2], hm1[2], hm2[2];
; #pragma unroll
;                 for (int bj = 0; bj < 2; ++bj) {
;                     const int cc = bj * DFF + ch + 4 * eh;
; #pragma unroll
;                     for (int j = 0; j < 3; ++j) w[bj][j] = *(const LAS f32x4*)(cwl + (2 * j + bj) * 128 + 4 * eh);
;                     bia[bj] = *(const LAS f32x4*)(cwl + (6 + bj) * 128 + 4 * eh);
;                     if (!prompt) { const float* ps = past + (size_t)((blk0 - MP) >> 6) * 2 * DFF2 + cc; hm2[bj] = *(const f32x4*)ps; hm1[bj] = *(const f32x4*)(ps + DFF2); }
;                     else if (ai == 0 && wr == 0) { hm1[bj] = (f32x4){0.f, 0.f, 0.f, 0.f}; hm2[bj] = hm1[bj]; }
;                     else { const int pb = ai * 2 + wr - 1; const LAS float* s = hl + (((pb * 4 + wc) * 2 + 0) * 4 + fq) * 16 + bj * 8 + 4 * eh; hm2[bj] = *(const LAS f32x4*)s; hm1[bj] = *(const LAS f32x4*)(s + 64); }
;                 }
;                 u32x2 pk[4]; f32x4 pr1[2], pr2[2];
; #pragma unroll
;                 for (int bj = 0; bj < 2; ++bj)
; #pragma unroll
;                     for (int e = 0; e < 4; ++e) { pr1[bj][e] = hm1[bj][e]; pr2[bj][e] = (fr == 0) ? hm2[bj][e] : hm1[bj][e]; }
; #pragma unroll
;                 for (int m = 0; m < 4; ++m) {
;                     f32x4 c[2];
; #pragma unroll
;                     for (int bj = 0; bj < 2; ++bj) {
;                         const f32x4 h0 = acc[ai][bj][m][eh]; f32x4 p1, p2;
; #pragma unroll
;                         for (int e = 0; e < 4; ++e) {
;                             const float r1 = dpp_ror1(h0[e]), r2 = dpp_ror2(h0[e]);
;                             p1[e] = (fr >= 1) ? r1 : pr1[bj][e]; p2[e] = (fr >= 2) ? r2 : pr2[bj][e];
;                             pr1[bj][e] = r1; pr2[bj][e] = r2;
;                         }
;                         c[bj] = bia[bj] + w[bj][0] * p2 + w[bj][1] * p1 + w[bj][2] * h0;
;                     }
;                     f32x4 o;
; #pragma unroll
;                     for (int e = 0; e < 4; ++e) o[e] = silu_f(c[0][e]) * c[1][e];
;                     pk[m].x = cvt_pk_bf16(o[0], o[1]); pk[m].y = cvt_pk_bf16(o[2], o[3]);
;                 }
.LBB0_1848:
	s_andn2_b64 vcc, exec, s[2:3]
	s_addk_i32 s37, 0x80
	s_cbranch_vccnz .LBB0_1850
	ds_read_b128 v[110:113], v191 offset:2080
	ds_read_b128 v[102:105], v191 offset:2336
.LBB0_1850:
	v_pk_mul_f32 v[46:47], v[46:47], v[192:193] op_sel_hi:[1,0]
	v_pk_mul_f32 v[116:117], v[34:35], v[192:193] op_sel_hi:[1,0]
	v_mov_b32_e32 v34, v193
	v_pk_mul_f32 v[48:49], v[48:49], v[192:193] op_sel_hi:[1,0]
	v_pk_mul_f32 v[44:45], v[44:45], v[34:35] op_sel_hi:[1,0]
	v_pk_mul_f32 v[42:43], v[42:43], v[34:35] op_sel_hi:[1,0]
	v_pk_mul_f32 v[118:119], v[32:33], v[34:35] op_sel_hi:[1,0]
	v_pk_mul_f32 v[120:121], v[30:31], v[34:35] op_sel_hi:[1,0]
	v_pk_mul_f32 v[34:35], v[38:39], v[190:191] op_sel_hi:[1,0]
	v_pk_mul_f32 v[30:31], v[28:29], v[190:191] op_sel_hi:[1,0]
	v_pk_mul_f32 v[28:29], v[26:27], v[190:191] op_sel_hi:[1,0]
	s_waitcnt lgkmcnt(4)
	s_and_b64 vcc, exec, s[8:9]
	s_cbranch_vccnz .Leu_j1850
	s_waitcnt vmcnt(0)
.Leu_j1850:
	v_cndmask_b32_e64 v27, v98, v106, s[10:11]
	v_cndmask_b32_e64 v39, v99, v107, s[10:11]
	v_cndmask_b32_e64 v106, v101, v109, s[10:11]
	s_waitcnt lgkmcnt(0)
	v_cndmask_b32_e64 v109, v104, v112, s[10:11]
	v_mov_b32_dpp v112, v46 row_ror:2 row_mask:0xf bank_mask:0xf bound_ctrl:1
	v_mov_b32_dpp v123, v47 row_ror:2 row_mask:0xf bank_mask:0xf bound_ctrl:1
	v_pk_mul_f32 v[32:33], v[40:41], v[190:191] op_sel_hi:[1,0]
	v_cndmask_b32_e64 v41, v100, v108, s[10:11]
	v_cndmask_b32_e64 v107, v102, v110, s[10:11]
	v_cndmask_b32_e64 v108, v103, v111, s[10:11]
	v_cndmask_b32_e64 v110, v105, v113, s[10:11]
	v_mov_b32_dpp v111, v46 row_ror:1 row_mask:0xf bank_mask:0xf bound_ctrl:1
	v_cndmask_b32_e64 v38, v27, v112, s[12:13]
	v_mov_b32_dpp v113, v47 row_ror:1 row_mask:0xf bank_mask:0xf bound_ctrl:1
	v_cndmask_b32_e64 v39, v39, v123, s[12:13]
	v_mov_b32_dpp v124, v48 row_ror:1 row_mask:0xf bank_mask:0xf bound_ctrl:1
	v_mov_b32_dpp v125, v48 row_ror:2 row_mask:0xf bank_mask:0xf bound_ctrl:1
	v_mov_b32_dpp v126, v49 row_ror:2 row_mask:0xf bank_mask:0xf bound_ctrl:1
	v_cndmask_b32_e64 v26, v111, v98, s[10:11]
	v_cndmask_b32_e64 v27, v113, v99, s[10:11]
	v_cndmask_b32_e64 v40, v124, v100, s[10:11]
	v_cndmask_b32_e64 v98, v41, v125, s[12:13]
	v_mov_b32_dpp v100, v49 row_ror:1 row_mask:0xf bank_mask:0xf bound_ctrl:1
	v_cndmask_b32_e64 v99, v106, v126, s[12:13]
	v_pk_fma_f32 v[38:39], v[70:71], v[38:39], v[82:83]
	v_cndmask_b32_e64 v41, v100, v101, s[10:11]
	v_pk_fma_f32 v[98:99], v[72:73], v[98:99], v[84:85]
	v_pk_fma_f32 v[26:27], v[66:67], v[26:27], v[38:39]
	v_mov_b32_dpp v106, v116 row_ror:2 row_mask:0xf bank_mask:0xf bound_ctrl:1
	v_pk_mul_f32 v[36:37], v[36:37], v[192:193] op_sel_hi:[1,0]
	v_pk_fma_f32 v[40:41], v[68:69], v[40:41], v[98:99]
	v_pk_fma_f32 v[26:27], v[46:47], v[62:63], v[26:27]
	v_mov_b32_dpp v101, v116 row_ror:1 row_mask:0xf bank_mask:0xf bound_ctrl:1
	v_cndmask_b32_e64 v46, v107, v106, s[12:13]
	v_mov_b32_dpp v107, v117 row_ror:2 row_mask:0xf bank_mask:0xf bound_ctrl:1
	v_pk_fma_f32 v[38:39], v[48:49], v[64:65], v[40:41]
	v_cndmask_b32_e64 v40, v101, v102, s[10:11]
	v_mov_b32_dpp v102, v117 row_ror:1 row_mask:0xf bank_mask:0xf bound_ctrl:1
	v_cndmask_b32_e64 v47, v108, v107, s[12:13]
	v_mov_b32_dpp v108, v36 row_ror:2 row_mask:0xf bank_mask:0xf bound_ctrl:1
	v_cndmask_b32_e64 v41, v102, v103, s[10:11]
	v_mov_b32_dpp v103, v36 row_ror:1 row_mask:0xf bank_mask:0xf bound_ctrl:1
	v_cndmask_b32_e64 v98, v109, v108, s[12:13]
	v_mov_b32_dpp v109, v37 row_ror:2 row_mask:0xf bank_mask:0xf bound_ctrl:1
	v_cndmask_b32_e64 v48, v103, v104, s[10:11]
	v_mov_b32_dpp v104, v37 row_ror:1 row_mask:0xf bank_mask:0xf bound_ctrl:1
	v_cndmask_b32_e64 v99, v110, v109, s[12:13]
	v_cndmask_b32_e64 v49, v104, v105, s[10:11]
	v_pk_fma_f32 v[98:99], v[92:93], v[98:99], v[96:97]
	v_pk_fma_f32 v[46:47], v[90:91], v[46:47], v[94:95]
	v_pk_fma_f32 v[48:49], v[88:89], v[48:49], v[98:99]
	v_pk_fma_f32 v[40:41], v[86:87], v[40:41], v[46:47]
	v_mul_f32_e32 v46, 0xbfb8aa3b, v26
	v_mul_f32_e32 v47, 0xbfb8aa3b, v27
	v_pk_fma_f32 v[36:37], v[36:37], v[60:61], v[48:49]
	v_mul_f32_e32 v48, 0xbfb8aa3b, v38
	v_mul_f32_e32 v49, 0xbfb8aa3b, v39
	v_exp_f32_e32 v46, v46
	v_exp_f32_e32 v47, v47
	v_exp_f32_e32 v48, v48
	v_exp_f32_e32 v49, v49
	v_add_f32_e32 v46, 1.0, v46
	v_add_f32_e32 v47, 1.0, v47
	v_add_f32_e32 v48, 1.0, v48
	v_add_f32_e32 v49, 1.0, v49
	v_rcp_f32_e32 v46, v46
	v_rcp_f32_e32 v47, v47
	v_rcp_f32_e32 v48, v48
	v_rcp_f32_e32 v49, v49
	v_pk_fma_f32 v[40:41], v[116:117], v[58:59], v[40:41]
	v_pk_mul_f32 v[26:27], v[26:27], v[46:47]
	v_mov_b32_dpp v99, v43 row_ror:2 row_mask:0xf bank_mask:0xf bound_ctrl:1
	v_pk_mul_f32 v[38:39], v[38:39], v[48:49]
	v_mov_b32_dpp v49, v42 row_ror:2 row_mask:0xf bank_mask:0xf bound_ctrl:1
	v_pk_mul_f32 v[26:27], v[26:27], v[40:41]
	v_pk_mul_f32 v[36:37], v[38:39], v[36:37]
	v_mov_b32_dpp v48, v42 row_ror:1 row_mask:0xf bank_mask:0xf bound_ctrl:1
	v_cndmask_b32_e64 v38, v112, v49, s[12:13]
	v_mov_b32_dpp v98, v43 row_ror:1 row_mask:0xf bank_mask:0xf bound_ctrl:1
	v_cndmask_b32_e64 v39, v123, v99, s[12:13]
	v_mov_b32_dpp v110, v44 row_ror:2 row_mask:0xf bank_mask:0xf bound_ctrl:1
	v_mov_b32_dpp v112, v45 row_ror:2 row_mask:0xf bank_mask:0xf bound_ctrl:1
	v_cvt_pk_bf16_f32 v26, v26, v27
	v_cvt_pk_bf16_f32 v27, v36, v37
	v_cndmask_b32_e64 v36, v48, v111, s[10:11]
	v_cndmask_b32_e64 v37, v98, v113, s[10:11]
	v_mov_b32_dpp v105, v44 row_ror:1 row_mask:0xf bank_mask:0xf bound_ctrl:1
	v_cndmask_b32_e64 v46, v125, v110, s[12:13]
	v_mov_b32_dpp v111, v45 row_ror:1 row_mask:0xf bank_mask:0xf bound_ctrl:1
	v_cndmask_b32_e64 v47, v126, v112, s[12:13]
	v_pk_fma_f32 v[38:39], v[70:71], v[38:39], v[82:83]
	v_cndmask_b32_e64 v40, v105, v124, s[10:11]
; __device__ __forceinline__ unsigned cvt_pk_bf16(float lo, float hi) { const f32x2 v = {lo, hi}; unsigned r = __builtin_bit_cast(unsigned, __builtin_convertvector(v, bf16x2_t)); asm volatile("" : "+v"(r)); return r; }
; __device__ __forceinline__ float silu_f(float x) { return x * __builtin_amdgcn_rcpf(1.0f + __expf(-x)); }
; __device__ __forceinline__ float dpp_ror1(float x) { return __builtin_bit_cast(float, __builtin_amdgcn_update_dpp(0, __builtin_bit_cast(int, x), 0x121, 0xf, 0xf, true)); }
; __device__ __forceinline__ float dpp_ror2(float x) { return __builtin_bit_cast(float, __builtin_amdgcn_update_dpp(0, __builtin_bit_cast(int, x), 0x122, 0xf, 0xf, true)); }
;     __device__ __forceinline__ void operator()(const f32x4 (&acc_)[2][2][4][2], const pg8::Unit& u, int wr, int wc, int fr, int fq) const {
;     ...
;                 for (int m = 0; m < 4; ++m) {
;                     f32x4 c[2];
; #pragma unroll
;                     for (int bj = 0; bj < 2; ++bj) {
;                         const f32x4 h0 = acc[ai][bj][m][eh]; f32x4 p1, p2;
; #pragma unroll
;                         for (int e = 0; e < 4; ++e) {
;                             const float r1 = dpp_ror1(h0[e]), r2 = dpp_ror2(h0[e]);
;                             p1[e] = (fr >= 1) ? r1 : pr1[bj][e]; p2[e] = (fr >= 2) ? r2 : pr2[bj][e];
;                             pr1[bj][e] = r1; pr2[bj][e] = r2;
;                         }
;                         c[bj] = bia[bj] + w[bj][0] * p2 + w[bj][1] * p1 + w[bj][2] * h0;
;                     }
;                     f32x4 o;
; #pragma unroll
;                     for (int e = 0; e < 4; ++e) o[e] = silu_f(c[0][e]) * c[1][e];
;                     pk[m].x = cvt_pk_bf16(o[0], o[1]); pk[m].y = cvt_pk_bf16(o[2], o[3]);
;                 }
	v_cndmask_b32_e64 v41, v111, v100, s[10:11]
	v_pk_fma_f32 v[46:47], v[72:73], v[46:47], v[84:85]
	v_pk_fma_f32 v[36:37], v[66:67], v[36:37], v[38:39]
	v_mov_b32_dpp v113, v120 row_ror:2 row_mask:0xf bank_mask:0xf bound_ctrl:1
	v_pk_fma_f32 v[40:41], v[68:69], v[40:41], v[46:47]
	v_pk_fma_f32 v[36:37], v[42:43], v[62:63], v[36:37]
	v_mov_b32_dpp v100, v120 row_ror:1 row_mask:0xf bank_mask:0xf bound_ctrl:1
	v_cndmask_b32_e64 v42, v106, v113, s[12:13]
	v_mov_b32_dpp v106, v121 row_ror:2 row_mask:0xf bank_mask:0xf bound_ctrl:1
	v_pk_fma_f32 v[38:39], v[44:45], v[64:65], v[40:41]
	v_cndmask_b32_e64 v40, v100, v101, s[10:11]
	v_mov_b32_dpp v101, v121 row_ror:1 row_mask:0xf bank_mask:0xf bound_ctrl:1
	v_cndmask_b32_e64 v43, v107, v106, s[12:13]
	v_mov_b32_dpp v107, v118 row_ror:2 row_mask:0xf bank_mask:0xf bound_ctrl:1
	v_cndmask_b32_e64 v41, v101, v102, s[10:11]
	v_mov_b32_dpp v102, v118 row_ror:1 row_mask:0xf bank_mask:0xf bound_ctrl:1
	v_cndmask_b32_e64 v46, v108, v107, s[12:13]
	v_mov_b32_dpp v108, v119 row_ror:2 row_mask:0xf bank_mask:0xf bound_ctrl:1
	v_cndmask_b32_e64 v44, v102, v103, s[10:11]
	v_mov_b32_dpp v103, v119 row_ror:1 row_mask:0xf bank_mask:0xf bound_ctrl:1
	v_cndmask_b32_e64 v47, v109, v108, s[12:13]
	v_pk_fma_f32 v[42:43], v[90:91], v[42:43], v[94:95]
	v_cndmask_b32_e64 v45, v103, v104, s[10:11]
	v_pk_fma_f32 v[46:47], v[92:93], v[46:47], v[96:97]
	v_pk_fma_f32 v[40:41], v[86:87], v[40:41], v[42:43]
	v_mul_f32_e32 v42, 0xbfb8aa3b, v36
	v_pk_fma_f32 v[44:45], v[88:89], v[44:45], v[46:47]
	v_exp_f32_e32 v46, v42
	v_mul_f32_e32 v42, 0xbfb8aa3b, v37
	v_exp_f32_e32 v47, v42
	v_pk_fma_f32 v[42:43], v[118:119], v[60:61], v[44:45]
	v_add_f32_e32 v44, 1.0, v46
	v_mul_f32_e32 v46, 0xbfb8aa3b, v38
	v_add_f32_e32 v45, 1.0, v47
	v_mul_f32_e32 v47, 0xbfb8aa3b, v39
	v_exp_f32_e32 v46, v46
	v_exp_f32_e32 v47, v47
	v_rcp_f32_e32 v44, v44
	v_rcp_f32_e32 v45, v45
	v_add_f32_e32 v46, 1.0, v46
	v_add_f32_e32 v47, 1.0, v47
	v_rcp_f32_e32 v46, v46
	v_rcp_f32_e32 v47, v47
	v_pk_fma_f32 v[40:41], v[120:121], v[58:59], v[40:41]
	v_pk_mul_f32 v[36:37], v[36:37], v[44:45]
	v_mov_b32_dpp v104, v33 row_ror:1 row_mask:0xf bank_mask:0xf bound_ctrl:1
	v_pk_mul_f32 v[38:39], v[38:39], v[46:47]
	v_pk_mul_f32 v[36:37], v[36:37], v[40:41]
	v_pk_mul_f32 v[38:39], v[38:39], v[42:43]
	v_mov_b32_dpp v46, v34 row_ror:1 row_mask:0xf bank_mask:0xf bound_ctrl:1
	v_mov_b32_dpp v47, v34 row_ror:2 row_mask:0xf bank_mask:0xf bound_ctrl:1
	v_cvt_pk_bf16_f32 v36, v36, v37
	v_cvt_pk_bf16_f32 v37, v38, v39
	v_cndmask_b32_e64 v38, v46, v48, s[10:11]
	v_cndmask_b32_e64 v40, v49, v47, s[12:13]
	v_mov_b32_dpp v48, v35 row_ror:1 row_mask:0xf bank_mask:0xf bound_ctrl:1
	v_mov_b32_dpp v49, v35 row_ror:2 row_mask:0xf bank_mask:0xf bound_ctrl:1
	v_cndmask_b32_e64 v39, v48, v98, s[10:11]
	v_cndmask_b32_e64 v41, v99, v49, s[12:13]
	v_mov_b32_dpp v98, v32 row_ror:1 row_mask:0xf bank_mask:0xf bound_ctrl:1
	v_mov_b32_dpp v99, v32 row_ror:2 row_mask:0xf bank_mask:0xf bound_ctrl:1
	v_cndmask_b32_e64 v42, v98, v105, s[10:11]
	v_mov_b32_dpp v105, v33 row_ror:2 row_mask:0xf bank_mask:0xf bound_ctrl:1
	v_pk_fma_f32 v[40:41], v[70:71], v[40:41], v[82:83]
	v_cndmask_b32_e64 v44, v110, v99, s[12:13]
	v_cndmask_b32_e64 v43, v104, v111, s[10:11]
	v_cndmask_b32_e64 v45, v112, v105, s[12:13]
	v_pk_fma_f32 v[38:39], v[66:67], v[38:39], v[40:41]
	v_mov_b32_dpp v109, v28 row_ror:1 row_mask:0xf bank_mask:0xf bound_ctrl:1
	v_mov_b32_dpp v111, v29 row_ror:2 row_mask:0xf bank_mask:0xf bound_ctrl:1
	v_pk_fma_f32 v[44:45], v[72:73], v[44:45], v[84:85]
	v_pk_fma_f32 v[34:35], v[34:35], v[62:63], v[38:39]
	v_cndmask_b32_e64 v38, v109, v100, s[10:11]
	v_mov_b32_dpp v100, v29 row_ror:1 row_mask:0xf bank_mask:0xf bound_ctrl:1
	v_cndmask_b32_e64 v41, v106, v111, s[12:13]
	v_mov_b32_dpp v106, v30 row_ror:2 row_mask:0xf bank_mask:0xf bound_ctrl:1
	v_pk_fma_f32 v[42:43], v[68:69], v[42:43], v[44:45]
	v_cndmask_b32_e64 v39, v100, v101, s[10:11]
	v_mov_b32_dpp v101, v30 row_ror:1 row_mask:0xf bank_mask:0xf bound_ctrl:1
	v_cndmask_b32_e64 v44, v107, v106, s[12:13]
	v_mov_b32_dpp v107, v31 row_ror:2 row_mask:0xf bank_mask:0xf bound_ctrl:1
	v_pk_fma_f32 v[32:33], v[32:33], v[64:65], v[42:43]
	v_mov_b32_dpp v110, v28 row_ror:2 row_mask:0xf bank_mask:0xf bound_ctrl:1
	v_cndmask_b32_e64 v42, v101, v102, s[10:11]
	v_mov_b32_dpp v102, v31 row_ror:1 row_mask:0xf bank_mask:0xf bound_ctrl:1
	v_cndmask_b32_e64 v45, v108, v107, s[12:13]
	v_cndmask_b32_e64 v40, v113, v110, s[12:13]
	v_cndmask_b32_e64 v43, v102, v103, s[10:11]
	v_pk_fma_f32 v[44:45], v[92:93], v[44:45], v[96:97]
	v_pk_fma_f32 v[40:41], v[90:91], v[40:41], v[94:95]
	v_pk_fma_f32 v[42:43], v[88:89], v[42:43], v[44:45]
	v_pk_fma_f32 v[38:39], v[86:87], v[38:39], v[40:41]
	v_mul_f32_e32 v40, 0xbfb8aa3b, v34
	v_mul_f32_e32 v41, 0xbfb8aa3b, v35
	v_pk_fma_f32 v[30:31], v[30:31], v[60:61], v[42:43]
	v_mul_f32_e32 v42, 0xbfb8aa3b, v32
	v_mul_f32_e32 v43, 0xbfb8aa3b, v33
; #define LAS __attribute__((address_space(3)))
; __device__ __forceinline__ float silu_f(float x) { return x * __builtin_amdgcn_rcpf(1.0f + __expf(-x)); }
;     __device__ __forceinline__ void operator()(const f32x4 (&acc_)[2][2][4][2], const pg8::Unit& u, int wr, int wc, int fr, int fq) const {
;     ...
;                 f32x4 w[2][3], bia[2], hm1[2], hm2[2];
; #pragma unroll
;                 for (int bj = 0; bj < 2; ++bj) {
;                     const int cc = bj * DFF + ch + 4 * eh;
; #pragma unroll
;                     for (int j = 0; j < 3; ++j) w[bj][j] = *(const LAS f32x4*)(cwl + (2 * j + bj) * 128 + 4 * eh);
;                     bia[bj] = *(const LAS f32x4*)(cwl + (6 + bj) * 128 + 4 * eh);
;                     if (!prompt) { const float* ps = past + (size_t)((blk0 - MP) >> 6) * 2 * DFF2 + cc; hm2[bj] = *(const f32x4*)ps; hm1[bj] = *(const f32x4*)(ps + DFF2); }
;                     else if (ai == 0 && wr == 0) { hm1[bj] = (f32x4){0.f, 0.f, 0.f, 0.f}; hm2[bj] = hm1[bj]; }
;                     else { const int pb = ai * 2 + wr - 1; const LAS float* s = hl + (((pb * 4 + wc) * 2 + 0) * 4 + fq) * 16 + bj * 8 + 4 * eh; hm2[bj] = *(const LAS f32x4*)s; hm1[bj] = *(const LAS f32x4*)(s + 64); }
;     ...
;                 for (int m = 0; m < 4; ++m) {
;                     f32x4 c[2];
; #pragma unroll
;                     for (int bj = 0; bj < 2; ++bj) {
;                         const f32x4 h0 = acc[ai][bj][m][eh]; f32x4 p1, p2;
; #pragma unroll
;                         for (int e = 0; e < 4; ++e) {
;                             const float r1 = dpp_ror1(h0[e]), r2 = dpp_ror2(h0[e]);
;                             p1[e] = (fr >= 1) ? r1 : pr1[bj][e]; p2[e] = (fr >= 2) ? r2 : pr2[bj][e];
;                             pr1[bj][e] = r1; pr2[bj][e] = r2;
;                         }
;                         c[bj] = bia[bj] + w[bj][0] * p2 + w[bj][1] * p1 + w[bj][2] * h0;
;                     }
;                     f32x4 o;
; #pragma unroll
;                     for (int e = 0; e < 4; ++e) o[e] = silu_f(c[0][e]) * c[1][e];
;                     pk[m].x = cvt_pk_bf16(o[0], o[1]); pk[m].y = cvt_pk_bf16(o[2], o[3]);
;                 }
; #pragma unroll
;                 for (int m = 0; m < 4; ++m) *(u32x2*)(act + (size_t)(blk0 + 16 * m + fr) * DFF + ch + 4 * eh) = pk[m];
	v_exp_f32_e32 v40, v40
	v_exp_f32_e32 v41, v41
	v_exp_f32_e32 v42, v42
	v_exp_f32_e32 v43, v43
	v_add_f32_e32 v40, 1.0, v40
	v_add_f32_e32 v41, 1.0, v41
	v_add_f32_e32 v42, 1.0, v42
	v_add_f32_e32 v43, 1.0, v43
	v_rcp_f32_e32 v40, v40
	v_rcp_f32_e32 v41, v41
	v_rcp_f32_e32 v42, v42
	v_rcp_f32_e32 v43, v43
	v_pk_fma_f32 v[28:29], v[28:29], v[58:59], v[38:39]
	v_pk_mul_f32 v[34:35], v[34:35], v[40:41]
	v_mov_b32_dpp v39, v81 row_ror:2 row_mask:0xf bank_mask:0xf bound_ctrl:1
	v_pk_mul_f32 v[32:33], v[32:33], v[42:43]
	v_pk_mul_f32 v[28:29], v[34:35], v[28:29]
	v_pk_mul_f32 v[30:31], v[32:33], v[30:31]
	v_cvt_pk_bf16_f32 v28, v28, v29
	v_cvt_pk_bf16_f32 v29, v30, v31
	v_mov_b32_dpp v31, v78 row_ror:2 row_mask:0xf bank_mask:0xf bound_ctrl:1
	v_mov_b32_dpp v33, v79 row_ror:2 row_mask:0xf bank_mask:0xf bound_ctrl:1
	v_mov_b32_dpp v35, v80 row_ror:2 row_mask:0xf bank_mask:0xf bound_ctrl:1
	v_mov_b32_dpp v30, v78 row_ror:1 row_mask:0xf bank_mask:0xf bound_ctrl:1
	v_cndmask_b32_e64 v32, v47, v31, s[12:13]
	v_mov_b32_dpp v31, v79 row_ror:1 row_mask:0xf bank_mask:0xf bound_ctrl:1
	v_cndmask_b32_e64 v33, v49, v33, s[12:13]
	v_mov_b32_dpp v34, v80 row_ror:1 row_mask:0xf bank_mask:0xf bound_ctrl:1
	v_cndmask_b32_e64 v38, v99, v35, s[12:13]
	v_mov_b32_dpp v35, v81 row_ror:1 row_mask:0xf bank_mask:0xf bound_ctrl:1
	v_cndmask_b32_e64 v39, v105, v39, s[12:13]
	v_cndmask_b32_e64 v30, v30, v46, s[10:11]
	v_cndmask_b32_e64 v31, v31, v48, s[10:11]
	v_cndmask_b32_e64 v34, v34, v98, s[10:11]
	v_cndmask_b32_e64 v35, v35, v104, s[10:11]
	v_pk_fma_f32 v[38:39], v[72:73], v[38:39], v[84:85]
	v_pk_fma_f32 v[32:33], v[70:71], v[32:33], v[82:83]
	v_mov_b32_dpp v41, v76 row_ror:2 row_mask:0xf bank_mask:0xf bound_ctrl:1
	v_pk_fma_f32 v[30:31], v[66:67], v[30:31], v[32:33]
	v_pk_fma_f32 v[32:33], v[68:69], v[34:35], v[38:39]
	v_mov_b32_dpp v35, v74 row_ror:2 row_mask:0xf bank_mask:0xf bound_ctrl:1
	v_mov_b32_dpp v39, v75 row_ror:2 row_mask:0xf bank_mask:0xf bound_ctrl:1
	v_mov_b32_dpp v43, v77 row_ror:2 row_mask:0xf bank_mask:0xf bound_ctrl:1
	v_mov_b32_dpp v34, v74 row_ror:1 row_mask:0xf bank_mask:0xf bound_ctrl:1
	v_cndmask_b32_e64 v38, v110, v35, s[12:13]
	v_mov_b32_dpp v35, v75 row_ror:1 row_mask:0xf bank_mask:0xf bound_ctrl:1
	v_cndmask_b32_e64 v39, v111, v39, s[12:13]
	v_mov_b32_dpp v40, v76 row_ror:1 row_mask:0xf bank_mask:0xf bound_ctrl:1
	v_cndmask_b32_e64 v42, v106, v41, s[12:13]
	v_mov_b32_dpp v41, v77 row_ror:1 row_mask:0xf bank_mask:0xf bound_ctrl:1
	v_cndmask_b32_e64 v43, v107, v43, s[12:13]
	v_pk_fma_f32 v[32:33], v[80:81], v[64:65], v[32:33]
	v_pk_fma_f32 v[30:31], v[78:79], v[62:63], v[30:31]
	v_cndmask_b32_e64 v34, v34, v109, s[10:11]
	v_cndmask_b32_e64 v35, v35, v100, s[10:11]
	v_cndmask_b32_e64 v40, v40, v101, s[10:11]
	v_cndmask_b32_e64 v41, v41, v102, s[10:11]
	v_pk_fma_f32 v[42:43], v[92:93], v[42:43], v[96:97]
	v_pk_fma_f32 v[38:39], v[90:91], v[38:39], v[94:95]
	v_or_b32_e32 v122, s37, v210
	v_pk_fma_f32 v[34:35], v[86:87], v[34:35], v[38:39]
	v_pk_fma_f32 v[38:39], v[88:89], v[40:41], v[42:43]
	v_mul_f32_e32 v40, 0xbfb8aa3b, v30
	v_mul_f32_e32 v41, 0xbfb8aa3b, v31
	v_mul_f32_e32 v42, 0xbfb8aa3b, v32
	v_mul_f32_e32 v43, 0xbfb8aa3b, v33
	v_exp_f32_e32 v40, v40
	v_exp_f32_e32 v41, v41
	v_exp_f32_e32 v42, v42
	v_exp_f32_e32 v43, v43
	v_add_f32_e32 v40, 1.0, v40
	v_add_f32_e32 v41, 1.0, v41
	v_add_f32_e32 v42, 1.0, v42
	v_add_f32_e32 v43, 1.0, v43
	v_rcp_f32_e32 v40, v40
	v_rcp_f32_e32 v41, v41
	v_rcp_f32_e32 v42, v42
	v_rcp_f32_e32 v43, v43
	v_pk_fma_f32 v[38:39], v[76:77], v[60:61], v[38:39]
	v_pk_fma_f32 v[34:35], v[74:75], v[58:59], v[34:35]
	v_pk_mul_f32 v[30:31], v[30:31], v[40:41]
	v_pk_mul_f32 v[32:33], v[32:33], v[42:43]
	v_pk_mul_f32 v[30:31], v[30:31], v[34:35]
	v_pk_mul_f32 v[32:33], v[32:33], v[38:39]
	v_cvt_pk_bf16_f32 v30, v30, v31
	v_cvt_pk_bf16_f32 v31, v32, v33
	v_mad_i64_i32 v[82:83], s[2:3], v122, s22, v[196:197]
	global_store_dwordx2 v[82:83], v[26:27], off
	v_or_b32_e32 v26, 16, v122
	v_mad_i64_i32 v[84:85], s[2:3], v26, s22, v[196:197]
	v_or_b32_e32 v26, 32, v122
	v_mad_i64_i32 v[86:87], s[2:3], v26, s22, v[196:197]
	global_store_dwordx2 v[84:85], v[36:37], off
	global_store_dwordx2 v[86:87], v[28:29], off
	ds_read_b128 v[38:41], v0 offset:16
	ds_read_b128 v[34:37], v0 offset:1040
	ds_read_b128 v[26:29], v0 offset:2064
	ds_read_b128 v[42:45], v0 offset:3088
	v_or_b32_e32 v32, 48, v122
	v_mad_i64_i32 v[88:89], s[2:3], v32, s22, v[196:197]
	s_and_b64 vcc, exec, s[8:9]
	s_mov_b64 s[2:3], -1
	global_store_dwordx2 v[88:89], v[30:31], off
	s_cbranch_vccnz .LBB0_1852
	v_add_co_u32_e32 v30, vcc, 0xb000, v114
	s_mov_b64 s[2:3], 0
	s_nop 0
	v_addc_co_u32_e32 v31, vcc, 0, v115, vcc
	global_load_dwordx4 v[74:77], v[114:115], off offset:16
	global_load_dwordx4 v[66:69], v[30:31], off offset:16
.LBB0_1852:
	s_andn2_b64 vcc, exec, s[2:3]
	s_cbranch_vccnz .LBB0_1854
	ds_read_b128 v[74:77], v191 offset:2064
	ds_read_b128 v[66:69], v191 offset:2320

; #define LAS __attribute__((address_space(3)))
;     __device__ __forceinline__ void operator()(const f32x4 (&acc_)[2][2][4][2], const pg8::Unit& u, int wr, int wc, int fr, int fq) const {
;     ...
;                 f32x4 w[2][3], bia[2], hm1[2], hm2[2];
; #pragma unroll
;                 for (int bj = 0; bj < 2; ++bj) {
;                     const int cc = bj * DFF + ch + 4 * eh;
; #pragma unroll
;                     for (int j = 0; j < 3; ++j) w[bj][j] = *(const LAS f32x4*)(cwl + (2 * j + bj) * 128 + 4 * eh);
;                     bia[bj] = *(const LAS f32x4*)(cwl + (6 + bj) * 128 + 4 * eh);
;                     if (!prompt) { const float* ps = past + (size_t)((blk0 - MP) >> 6) * 2 * DFF2 + cc; hm2[bj] = *(const f32x4*)ps; hm1[bj] = *(const f32x4*)(ps + DFF2); }
;                     else if (ai == 0 && wr == 0) { hm1[bj] = (f32x4){0.f, 0.f, 0.f, 0.f}; hm2[bj] = hm1[bj]; }
;                     else { const int pb = ai * 2 + wr - 1; const LAS float* s = hl + (((pb * 4 + wc) * 2 + 0) * 4 + fq) * 16 + bj * 8 + 4 * eh; hm2[bj] = *(const LAS f32x4*)s; hm1[bj] = *(const LAS f32x4*)(s + 64); }
;                 }
;                 u32x2 pk[4]; f32x4 pr1[2], pr2[2];
; #pragma unroll
;                 for (int bj = 0; bj < 2; ++bj)
; #pragma unroll
;                     for (int e = 0; e < 4; ++e) { pr1[bj][e] = hm1[bj][e]; pr2[bj][e] = (fr == 0) ? hm2[bj][e] : hm1[bj][e]; }
; #pragma unroll
;                 for (int m = 0; m < 4; ++m) {
;                     f32x4 c[2];
; #pragma unroll
;                     for (int bj = 0; bj < 2; ++bj) {
;                         const f32x4 h0 = acc[ai][bj][m][eh]; f32x4 p1, p2;
; #pragma unroll
;                         for (int e = 0; e < 4; ++e) {
;                             const float r1 = dpp_ror1(h0[e]), r2 = dpp_ror2(h0[e]);
;                             p1[e] = (fr >= 1) ? r1 : pr1[bj][e]; p2[e] = (fr >= 2) ? r2 : pr2[bj][e];
;                             pr1[bj][e] = r1; pr2[bj][e] = r2;
;                         }
;                         c[bj] = bia[bj] + w[bj][0] * p2 + w[bj][1] * p1 + w[bj][2] * h0;
;                     }
;                     f32x4 o;
; #pragma unroll
;                     for (int e = 0; e < 4; ++e) o[e] = silu_f(c[0][e]) * c[1][e];
;                     pk[m].x = cvt_pk_bf16(o[0], o[1]); pk[m].y = cvt_pk_bf16(o[2], o[3]);
;                 }
.LBB0_1856:
	s_andn2_b64 vcc, exec, s[2:3]
	s_cbranch_vccnz .LBB0_1858
	ds_read_b128 v[78:81], v191 offset:2096
	ds_read_b128 v[70:73], v191 offset:2352
.LBB0_1858:
	v_mov_b32_e32 v90, v192
	v_mov_b32_e32 v91, v192
	v_mov_b32_e32 v92, v193
	v_mov_b32_e32 v93, v193
	v_mov_b32_e32 v191, v190
	v_mov_b32_e32 v94, v192
	v_mov_b32_e32 v95, v192
	v_pk_mul_f32 v[22:23], v[22:23], v[90:91]
	v_pk_mul_f32 v[24:25], v[24:25], v[94:95]
	v_pk_mul_f32 v[90:91], v[10:11], v[90:91]
	v_mov_b32_e32 v192, v193
	v_pk_mul_f32 v[18:19], v[18:19], v[92:93]
	v_pk_mul_f32 v[92:93], v[6:7], v[92:93]
	v_mov_b32_e32 v6, v190
	v_mov_b32_e32 v7, v190
	v_pk_mul_f32 v[10:11], v[14:15], v[190:191]
	s_waitcnt lgkmcnt(4)
	s_and_b64 vcc, exec, s[8:9]
	s_cbranch_vccnz .Leu_j1858
	s_waitcnt vmcnt(0)
.Leu_j1858:
	v_cndmask_b32_e64 v0, v66, v74, s[10:11]
	v_cndmask_b32_e64 v15, v67, v75, s[10:11]
	v_cndmask_b32_e64 v74, v69, v77, s[10:11]
	s_waitcnt lgkmcnt(0)
	v_cndmask_b32_e64 v75, v70, v78, s[10:11]
	v_cndmask_b32_e64 v77, v72, v80, s[10:11]
	v_cndmask_b32_e64 v78, v73, v81, s[10:11]
	v_mov_b32_dpp v80, v22 row_ror:2 row_mask:0xf bank_mask:0xf bound_ctrl:1
	v_mov_b32_dpp v81, v23 row_ror:2 row_mask:0xf bank_mask:0xf bound_ctrl:1
	v_pk_mul_f32 v[12:13], v[12:13], v[94:95]
	v_pk_mul_f32 v[94:95], v[8:9], v[192:193]
	v_pk_mul_f32 v[8:9], v[16:17], v[6:7]
	v_cndmask_b32_e64 v17, v68, v76, s[10:11]
	v_cndmask_b32_e64 v76, v71, v79, s[10:11]
	v_mov_b32_dpp v79, v22 row_ror:1 row_mask:0xf bank_mask:0xf bound_ctrl:1
	v_cndmask_b32_e64 v14, v0, v80, s[12:13]
	v_mov_b32_dpp v0, v23 row_ror:1 row_mask:0xf bank_mask:0xf bound_ctrl:1
	v_cndmask_b32_e64 v15, v15, v81, s[12:13]
	v_mov_b32_dpp v96, v24 row_ror:1 row_mask:0xf bank_mask:0xf bound_ctrl:1
	v_mov_b32_dpp v97, v24 row_ror:2 row_mask:0xf bank_mask:0xf bound_ctrl:1
	v_mov_b32_dpp v98, v25 row_ror:2 row_mask:0xf bank_mask:0xf bound_ctrl:1
	v_pk_mul_f32 v[6:7], v[4:5], v[6:7]
	v_pk_mul_f32 v[4:5], v[2:3], v[190:191]
	v_cndmask_b32_e64 v2, v79, v66, s[10:11]
	v_cndmask_b32_e64 v3, v0, v67, s[10:11]
	v_cndmask_b32_e64 v16, v96, v68, s[10:11]
	v_cndmask_b32_e64 v66, v17, v97, s[12:13]
	v_mov_b32_dpp v68, v25 row_ror:1 row_mask:0xf bank_mask:0xf bound_ctrl:1
	v_cndmask_b32_e64 v67, v74, v98, s[12:13]
	v_pk_fma_f32 v[14:15], v[38:39], v[14:15], v[42:43]
	v_cndmask_b32_e64 v17, v68, v69, s[10:11]
	v_pk_fma_f32 v[66:67], v[40:41], v[66:67], v[44:45]
	v_pk_fma_f32 v[2:3], v[34:35], v[2:3], v[14:15]
	v_mov_b32_dpp v74, v90 row_ror:2 row_mask:0xf bank_mask:0xf bound_ctrl:1
	v_pk_fma_f32 v[16:17], v[36:37], v[16:17], v[66:67]
	v_pk_fma_f32 v[2:3], v[22:23], v[26:27], v[2:3]
	v_mov_b32_dpp v69, v90 row_ror:1 row_mask:0xf bank_mask:0xf bound_ctrl:1
	v_cndmask_b32_e64 v22, v75, v74, s[12:13]
	v_mov_b32_dpp v75, v91 row_ror:2 row_mask:0xf bank_mask:0xf bound_ctrl:1
	v_pk_fma_f32 v[14:15], v[24:25], v[28:29], v[16:17]
	v_cndmask_b32_e64 v16, v69, v70, s[10:11]
	v_mov_b32_dpp v70, v91 row_ror:1 row_mask:0xf bank_mask:0xf bound_ctrl:1
	v_cndmask_b32_e64 v23, v76, v75, s[12:13]
	v_mov_b32_dpp v76, v12 row_ror:2 row_mask:0xf bank_mask:0xf bound_ctrl:1
	v_cndmask_b32_e64 v17, v70, v71, s[10:11]
	v_mov_b32_dpp v71, v12 row_ror:1 row_mask:0xf bank_mask:0xf bound_ctrl:1
	v_cndmask_b32_e64 v66, v77, v76, s[12:13]
	v_mov_b32_dpp v77, v13 row_ror:2 row_mask:0xf bank_mask:0xf bound_ctrl:1
	v_cndmask_b32_e64 v24, v71, v72, s[10:11]
	v_mov_b32_dpp v72, v13 row_ror:1 row_mask:0xf bank_mask:0xf bound_ctrl:1
	v_cndmask_b32_e64 v67, v78, v77, s[12:13]
	v_cndmask_b32_e64 v25, v72, v73, s[10:11]
	v_pk_fma_f32 v[66:67], v[60:61], v[66:67], v[64:65]
	v_pk_fma_f32 v[22:23], v[58:59], v[22:23], v[62:63]
	v_pk_fma_f32 v[24:25], v[48:49], v[24:25], v[66:67]
	v_pk_fma_f32 v[16:17], v[46:47], v[16:17], v[22:23]
	v_mul_f32_e32 v22, 0xbfb8aa3b, v2
	v_mul_f32_e32 v23, 0xbfb8aa3b, v3
	v_pk_fma_f32 v[12:13], v[12:13], v[32:33], v[24:25]
	v_mul_f32_e32 v24, 0xbfb8aa3b, v14
	v_mul_f32_e32 v25, 0xbfb8aa3b, v15
	v_exp_f32_e32 v22, v22
	v_exp_f32_e32 v23, v23
	v_exp_f32_e32 v24, v24
	v_exp_f32_e32 v25, v25
	v_add_f32_e32 v22, 1.0, v22
	v_add_f32_e32 v23, 1.0, v23
	v_add_f32_e32 v24, 1.0, v24
	v_add_f32_e32 v25, 1.0, v25
	v_rcp_f32_e32 v22, v22
	v_rcp_f32_e32 v23, v23
	v_rcp_f32_e32 v24, v24
	v_rcp_f32_e32 v25, v25
	v_pk_fma_f32 v[16:17], v[90:91], v[30:31], v[16:17]
	v_pk_mul_f32 v[2:3], v[2:3], v[22:23]
	v_pk_mul_f32 v[20:21], v[20:21], v[192:193]
	v_pk_mul_f32 v[14:15], v[14:15], v[24:25]
	v_pk_mul_f32 v[2:3], v[2:3], v[16:17]
	v_pk_mul_f32 v[12:13], v[14:15], v[12:13]
	v_mov_b32_dpp v24, v18 row_ror:1 row_mask:0xf bank_mask:0xf bound_ctrl:1
	v_mov_b32_dpp v25, v18 row_ror:2 row_mask:0xf bank_mask:0xf bound_ctrl:1
	v_mov_b32_dpp v67, v19 row_ror:2 row_mask:0xf bank_mask:0xf bound_ctrl:1
	v_cvt_pk_bf16_f32 v2, v2, v3
	v_cvt_pk_bf16_f32 v3, v12, v13
	v_cndmask_b32_e64 v12, v24, v79, s[10:11]
	v_cndmask_b32_e64 v14, v80, v25, s[12:13]
	v_mov_b32_dpp v66, v19 row_ror:1 row_mask:0xf bank_mask:0xf bound_ctrl:1
	v_cndmask_b32_e64 v15, v81, v67, s[12:13]
	v_mov_b32_dpp v73, v20 row_ror:2 row_mask:0xf bank_mask:0xf bound_ctrl:1
	v_mov_b32_dpp v79, v21 row_ror:2 row_mask:0xf bank_mask:0xf bound_ctrl:1
	v_cndmask_b32_e64 v13, v66, v0, s[10:11]
	v_mov_b32_dpp v0, v20 row_ror:1 row_mask:0xf bank_mask:0xf bound_ctrl:1
	v_cndmask_b32_e64 v22, v97, v73, s[12:13]
	v_mov_b32_dpp v78, v21 row_ror:1 row_mask:0xf bank_mask:0xf bound_ctrl:1
	v_cndmask_b32_e64 v23, v98, v79, s[12:13]
	v_pk_fma_f32 v[14:15], v[38:39], v[14:15], v[42:43]
	v_cndmask_b32_e64 v16, v0, v96, s[10:11]
	v_cndmask_b32_e64 v17, v78, v68, s[10:11]
	v_pk_fma_f32 v[22:23], v[40:41], v[22:23], v[44:45]
	v_pk_fma_f32 v[12:13], v[34:35], v[12:13], v[14:15]
; __device__ __forceinline__ unsigned cvt_pk_bf16(float lo, float hi) { const f32x2 v = {lo, hi}; unsigned r = __builtin_bit_cast(unsigned, __builtin_convertvector(v, bf16x2_t)); asm volatile("" : "+v"(r)); return r; }
; __device__ __forceinline__ float silu_f(float x) { return x * __builtin_amdgcn_rcpf(1.0f + __expf(-x)); }
; __device__ __forceinline__ float dpp_ror1(float x) { return __builtin_bit_cast(float, __builtin_amdgcn_update_dpp(0, __builtin_bit_cast(int, x), 0x121, 0xf, 0xf, true)); }
; __device__ __forceinline__ float dpp_ror2(float x) { return __builtin_bit_cast(float, __builtin_amdgcn_update_dpp(0, __builtin_bit_cast(int, x), 0x122, 0xf, 0xf, true)); }
;     __device__ __forceinline__ void operator()(const f32x4 (&acc_)[2][2][4][2], const pg8::Unit& u, int wr, int wc, int fr, int fq) const {
;     ...
;                 for (int m = 0; m < 4; ++m) {
;                     f32x4 c[2];
; #pragma unroll
;                     for (int bj = 0; bj < 2; ++bj) {
;                         const f32x4 h0 = acc[ai][bj][m][eh]; f32x4 p1, p2;
; #pragma unroll
;                         for (int e = 0; e < 4; ++e) {
;                             const float r1 = dpp_ror1(h0[e]), r2 = dpp_ror2(h0[e]);
;                             p1[e] = (fr >= 1) ? r1 : pr1[bj][e]; p2[e] = (fr >= 2) ? r2 : pr2[bj][e];
;                             pr1[bj][e] = r1; pr2[bj][e] = r2;
;                         }
;                         c[bj] = bia[bj] + w[bj][0] * p2 + w[bj][1] * p1 + w[bj][2] * h0;
;                     }
;                     f32x4 o;
; #pragma unroll
;                     for (int e = 0; e < 4; ++e) o[e] = silu_f(c[0][e]) * c[1][e];
;                     pk[m].x = cvt_pk_bf16(o[0], o[1]); pk[m].y = cvt_pk_bf16(o[2], o[3]);
;                 }
	v_mov_b32_dpp v80, v92 row_ror:2 row_mask:0xf bank_mask:0xf bound_ctrl:1
	v_pk_fma_f32 v[16:17], v[36:37], v[16:17], v[22:23]
	v_pk_fma_f32 v[12:13], v[18:19], v[26:27], v[12:13]
	v_mov_b32_dpp v68, v92 row_ror:1 row_mask:0xf bank_mask:0xf bound_ctrl:1
	v_cndmask_b32_e64 v18, v74, v80, s[12:13]
	v_mov_b32_dpp v74, v93 row_ror:2 row_mask:0xf bank_mask:0xf bound_ctrl:1
	v_pk_fma_f32 v[14:15], v[20:21], v[28:29], v[16:17]
	v_cndmask_b32_e64 v16, v68, v69, s[10:11]
	v_mov_b32_dpp v69, v93 row_ror:1 row_mask:0xf bank_mask:0xf bound_ctrl:1
	v_cndmask_b32_e64 v19, v75, v74, s[12:13]
	v_mov_b32_dpp v75, v94 row_ror:2 row_mask:0xf bank_mask:0xf bound_ctrl:1
	v_cndmask_b32_e64 v17, v69, v70, s[10:11]
	v_mov_b32_dpp v70, v94 row_ror:1 row_mask:0xf bank_mask:0xf bound_ctrl:1
	v_cndmask_b32_e64 v22, v76, v75, s[12:13]
	v_mov_b32_dpp v76, v95 row_ror:2 row_mask:0xf bank_mask:0xf bound_ctrl:1
	v_cndmask_b32_e64 v20, v70, v71, s[10:11]
	v_mov_b32_dpp v71, v95 row_ror:1 row_mask:0xf bank_mask:0xf bound_ctrl:1
	v_cndmask_b32_e64 v23, v77, v76, s[12:13]
	v_pk_fma_f32 v[18:19], v[58:59], v[18:19], v[62:63]
	v_cndmask_b32_e64 v21, v71, v72, s[10:11]
	v_pk_fma_f32 v[22:23], v[60:61], v[22:23], v[64:65]
	v_pk_fma_f32 v[16:17], v[46:47], v[16:17], v[18:19]
	v_mul_f32_e32 v18, 0xbfb8aa3b, v12
	v_pk_fma_f32 v[20:21], v[48:49], v[20:21], v[22:23]
	v_exp_f32_e32 v22, v18
	v_mul_f32_e32 v18, 0xbfb8aa3b, v13
	v_exp_f32_e32 v23, v18
	v_pk_fma_f32 v[18:19], v[94:95], v[32:33], v[20:21]
	v_add_f32_e32 v20, 1.0, v22
	v_mul_f32_e32 v22, 0xbfb8aa3b, v14
	v_add_f32_e32 v21, 1.0, v23
	v_mul_f32_e32 v23, 0xbfb8aa3b, v15
	v_exp_f32_e32 v22, v22
	v_exp_f32_e32 v23, v23
	v_rcp_f32_e32 v20, v20
	v_rcp_f32_e32 v21, v21
	v_add_f32_e32 v22, 1.0, v22
	v_add_f32_e32 v23, 1.0, v23
	v_rcp_f32_e32 v22, v22
	v_rcp_f32_e32 v23, v23
	v_pk_fma_f32 v[16:17], v[92:93], v[30:31], v[16:17]
	v_pk_mul_f32 v[12:13], v[12:13], v[20:21]
	v_mov_b32_dpp v72, v9 row_ror:2 row_mask:0xf bank_mask:0xf bound_ctrl:1
	v_pk_mul_f32 v[14:15], v[14:15], v[22:23]
	v_pk_mul_f32 v[12:13], v[12:13], v[16:17]
	v_pk_mul_f32 v[14:15], v[14:15], v[18:19]
	v_mov_b32_dpp v22, v10 row_ror:1 row_mask:0xf bank_mask:0xf bound_ctrl:1
	v_mov_b32_dpp v23, v10 row_ror:2 row_mask:0xf bank_mask:0xf bound_ctrl:1
	v_cvt_pk_bf16_f32 v12, v12, v13
	v_cvt_pk_bf16_f32 v13, v14, v15
	v_cndmask_b32_e64 v14, v22, v24, s[10:11]
	v_cndmask_b32_e64 v16, v25, v23, s[12:13]
	v_mov_b32_dpp v24, v11 row_ror:1 row_mask:0xf bank_mask:0xf bound_ctrl:1
	v_mov_b32_dpp v25, v11 row_ror:2 row_mask:0xf bank_mask:0xf bound_ctrl:1
	v_cndmask_b32_e64 v15, v24, v66, s[10:11]
	v_cndmask_b32_e64 v17, v67, v25, s[12:13]
	v_mov_b32_dpp v66, v8 row_ror:1 row_mask:0xf bank_mask:0xf bound_ctrl:1
	v_mov_b32_dpp v67, v8 row_ror:2 row_mask:0xf bank_mask:0xf bound_ctrl:1
	v_cndmask_b32_e64 v18, v66, v0, s[10:11]
	v_mov_b32_dpp v0, v9 row_ror:1 row_mask:0xf bank_mask:0xf bound_ctrl:1
	v_pk_fma_f32 v[16:17], v[38:39], v[16:17], v[42:43]
	v_cndmask_b32_e64 v20, v73, v67, s[12:13]
	v_cndmask_b32_e64 v19, v0, v78, s[10:11]
	v_cndmask_b32_e64 v21, v79, v72, s[12:13]
	v_pk_fma_f32 v[14:15], v[34:35], v[14:15], v[16:17]
	v_mov_b32_dpp v73, v4 row_ror:1 row_mask:0xf bank_mask:0xf bound_ctrl:1
	v_mov_b32_dpp v78, v5 row_ror:2 row_mask:0xf bank_mask:0xf bound_ctrl:1
	v_pk_fma_f32 v[20:21], v[40:41], v[20:21], v[44:45]
	v_pk_fma_f32 v[10:11], v[10:11], v[26:27], v[14:15]
	v_cndmask_b32_e64 v14, v73, v68, s[10:11]
	v_mov_b32_dpp v68, v5 row_ror:1 row_mask:0xf bank_mask:0xf bound_ctrl:1
	v_cndmask_b32_e64 v17, v74, v78, s[12:13]
	v_mov_b32_dpp v74, v6 row_ror:2 row_mask:0xf bank_mask:0xf bound_ctrl:1
	v_pk_fma_f32 v[18:19], v[36:37], v[18:19], v[20:21]
	v_cndmask_b32_e64 v15, v68, v69, s[10:11]
	v_mov_b32_dpp v69, v6 row_ror:1 row_mask:0xf bank_mask:0xf bound_ctrl:1
	v_cndmask_b32_e64 v20, v75, v74, s[12:13]
	v_mov_b32_dpp v75, v7 row_ror:2 row_mask:0xf bank_mask:0xf bound_ctrl:1
	v_pk_fma_f32 v[8:9], v[8:9], v[28:29], v[18:19]
	v_mov_b32_dpp v77, v4 row_ror:2 row_mask:0xf bank_mask:0xf bound_ctrl:1
	v_cndmask_b32_e64 v18, v69, v70, s[10:11]
	v_mov_b32_dpp v70, v7 row_ror:1 row_mask:0xf bank_mask:0xf bound_ctrl:1
	v_cndmask_b32_e64 v21, v76, v75, s[12:13]
	v_cndmask_b32_e64 v16, v80, v77, s[12:13]
	v_cndmask_b32_e64 v19, v70, v71, s[10:11]
	v_pk_fma_f32 v[20:21], v[60:61], v[20:21], v[64:65]
	v_pk_fma_f32 v[16:17], v[58:59], v[16:17], v[62:63]
; __device__ __forceinline__ unsigned cvt_pk_bf16(float lo, float hi) { const f32x2 v = {lo, hi}; unsigned r = __builtin_bit_cast(unsigned, __builtin_convertvector(v, bf16x2_t)); asm volatile("" : "+v"(r)); return r; }
; __device__ __forceinline__ float silu_f(float x) { return x * __builtin_amdgcn_rcpf(1.0f + __expf(-x)); }
; __device__ __forceinline__ float dpp_ror1(float x) { return __builtin_bit_cast(float, __builtin_amdgcn_update_dpp(0, __builtin_bit_cast(int, x), 0x121, 0xf, 0xf, true)); }
; __device__ __forceinline__ float dpp_ror2(float x) { return __builtin_bit_cast(float, __builtin_amdgcn_update_dpp(0, __builtin_bit_cast(int, x), 0x122, 0xf, 0xf, true)); }
;     __device__ __forceinline__ void operator()(const f32x4 (&acc_)[2][2][4][2], const pg8::Unit& u, int wr, int wc, int fr, int fq) const {
;     ...
;                 for (int m = 0; m < 4; ++m) {
;                     f32x4 c[2];
; #pragma unroll
;                     for (int bj = 0; bj < 2; ++bj) {
;                         const f32x4 h0 = acc[ai][bj][m][eh]; f32x4 p1, p2;
; #pragma unroll
;                         for (int e = 0; e < 4; ++e) {
;                             const float r1 = dpp_ror1(h0[e]), r2 = dpp_ror2(h0[e]);
;                             p1[e] = (fr >= 1) ? r1 : pr1[bj][e]; p2[e] = (fr >= 2) ? r2 : pr2[bj][e];
;                             pr1[bj][e] = r1; pr2[bj][e] = r2;
;                         }
;                         c[bj] = bia[bj] + w[bj][0] * p2 + w[bj][1] * p1 + w[bj][2] * h0;
;                     }
;                     f32x4 o;
; #pragma unroll
;                     for (int e = 0; e < 4; ++e) o[e] = silu_f(c[0][e]) * c[1][e];
;                     pk[m].x = cvt_pk_bf16(o[0], o[1]); pk[m].y = cvt_pk_bf16(o[2], o[3]);
;                 }
; #pragma unroll
;                 for (int m = 0; m < 4; ++m) *(u32x2*)(act + (size_t)(blk0 + 16 * m + fr) * DFF + ch + 4 * eh) = pk[m];
	v_pk_fma_f32 v[18:19], v[48:49], v[18:19], v[20:21]
	v_pk_fma_f32 v[14:15], v[46:47], v[14:15], v[16:17]
	v_mul_f32_e32 v16, 0xbfb8aa3b, v10
	v_mul_f32_e32 v17, 0xbfb8aa3b, v11
	v_pk_fma_f32 v[6:7], v[6:7], v[32:33], v[18:19]
	v_mul_f32_e32 v18, 0xbfb8aa3b, v8
	v_mul_f32_e32 v19, 0xbfb8aa3b, v9
	v_exp_f32_e32 v16, v16
	v_exp_f32_e32 v17, v17
	v_exp_f32_e32 v18, v18
	v_exp_f32_e32 v19, v19
	v_add_f32_e32 v16, 1.0, v16
	v_add_f32_e32 v17, 1.0, v17
	v_add_f32_e32 v18, 1.0, v18
	v_add_f32_e32 v19, 1.0, v19
	v_rcp_f32_e32 v16, v16
	v_rcp_f32_e32 v17, v17
	v_rcp_f32_e32 v18, v18
	v_rcp_f32_e32 v19, v19
	v_pk_fma_f32 v[4:5], v[4:5], v[30:31], v[14:15]
	v_pk_mul_f32 v[10:11], v[10:11], v[16:17]
	v_mov_b32_dpp v15, v57 row_ror:2 row_mask:0xf bank_mask:0xf bound_ctrl:1
	v_pk_mul_f32 v[8:9], v[8:9], v[18:19]
	v_pk_mul_f32 v[4:5], v[10:11], v[4:5]
	v_pk_mul_f32 v[6:7], v[8:9], v[6:7]
	v_mov_b32_dpp v11, v56 row_ror:2 row_mask:0xf bank_mask:0xf bound_ctrl:1
	v_cvt_pk_bf16_f32 v4, v4, v5
	v_cvt_pk_bf16_f32 v5, v6, v7
	v_mov_b32_dpp v7, v54 row_ror:2 row_mask:0xf bank_mask:0xf bound_ctrl:1
	v_mov_b32_dpp v9, v55 row_ror:2 row_mask:0xf bank_mask:0xf bound_ctrl:1
	v_cndmask_b32_e64 v14, v67, v11, s[12:13]
	v_mov_b32_dpp v11, v57 row_ror:1 row_mask:0xf bank_mask:0xf bound_ctrl:1
	v_mov_b32_dpp v6, v54 row_ror:1 row_mask:0xf bank_mask:0xf bound_ctrl:1
	v_cndmask_b32_e64 v8, v23, v7, s[12:13]
	v_mov_b32_dpp v7, v55 row_ror:1 row_mask:0xf bank_mask:0xf bound_ctrl:1
	v_cndmask_b32_e64 v9, v25, v9, s[12:13]
	v_cndmask_b32_e64 v11, v11, v0, s[10:11]
	v_mov_b32_dpp v0, v50 row_ror:1 row_mask:0xf bank_mask:0xf bound_ctrl:1
	v_cndmask_b32_e64 v6, v6, v22, s[10:11]
	v_cndmask_b32_e64 v7, v7, v24, s[10:11]
	v_mov_b32_dpp v17, v50 row_ror:2 row_mask:0xf bank_mask:0xf bound_ctrl:1
	v_cndmask_b32_e64 v16, v0, v73, s[10:11]
	v_mov_b32_dpp v0, v51 row_ror:1 row_mask:0xf bank_mask:0xf bound_ctrl:1
	v_pk_fma_f32 v[8:9], v[38:39], v[8:9], v[42:43]
	v_mov_b32_dpp v10, v56 row_ror:1 row_mask:0xf bank_mask:0xf bound_ctrl:1
	v_cndmask_b32_e64 v15, v72, v15, s[12:13]
	v_cndmask_b32_e64 v18, v77, v17, s[12:13]
	v_mov_b32_dpp v19, v51 row_ror:2 row_mask:0xf bank_mask:0xf bound_ctrl:1
	v_cndmask_b32_e64 v17, v0, v68, s[10:11]
	v_mov_b32_dpp v0, v52 row_ror:1 row_mask:0xf bank_mask:0xf bound_ctrl:1
	v_pk_fma_f32 v[6:7], v[34:35], v[6:7], v[8:9]
	v_cndmask_b32_e64 v10, v10, v66, s[10:11]
	v_cndmask_b32_e64 v19, v78, v19, s[12:13]
	v_mov_b32_dpp v21, v52 row_ror:2 row_mask:0xf bank_mask:0xf bound_ctrl:1
	v_cndmask_b32_e64 v20, v0, v69, s[10:11]
	v_mov_b32_dpp v0, v53 row_ror:1 row_mask:0xf bank_mask:0xf bound_ctrl:1
	v_pk_fma_f32 v[14:15], v[40:41], v[14:15], v[44:45]
	v_pk_fma_f32 v[6:7], v[54:55], v[26:27], v[6:7]
	v_cndmask_b32_e64 v22, v74, v21, s[12:13]
	v_cndmask_b32_e64 v21, v0, v70, s[10:11]
	v_pk_fma_f32 v[8:9], v[36:37], v[10:11], v[14:15]
	v_pk_fma_f32 v[14:15], v[58:59], v[18:19], v[62:63]
	v_mul_f32_e32 v0, 0xbfb8aa3b, v6
	v_pk_fma_f32 v[14:15], v[46:47], v[16:17], v[14:15]
	v_exp_f32_e32 v0, v0
	v_mul_f32_e32 v16, 0xbfb8aa3b, v7
	v_exp_f32_e32 v17, v16
	v_pk_fma_f32 v[8:9], v[56:57], v[28:29], v[8:9]
	v_add_f32_e32 v0, 1.0, v0
	v_rcp_f32_e32 v16, v0
	v_add_f32_e32 v0, 1.0, v17
	v_mul_f32_e32 v17, 0xbfb8aa3b, v8
	v_exp_f32_e32 v18, v17
	v_mul_f32_e32 v17, 0xbfb8aa3b, v9
	v_exp_f32_e32 v19, v17
	v_rcp_f32_e32 v17, v0
	v_add_f32_e32 v0, 1.0, v18
	v_rcp_f32_e32 v18, v0
	v_add_f32_e32 v0, 1.0, v19
	v_mov_b32_dpp v23, v53 row_ror:2 row_mask:0xf bank_mask:0xf bound_ctrl:1
	v_rcp_f32_e32 v19, v0
	v_cndmask_b32_e64 v23, v75, v23, s[12:13]
	v_pk_fma_f32 v[10:11], v[60:61], v[22:23], v[64:65]
	v_pk_fma_f32 v[14:15], v[50:51], v[30:31], v[14:15]
	v_pk_fma_f32 v[10:11], v[48:49], v[20:21], v[10:11]
	v_pk_mul_f32 v[6:7], v[6:7], v[16:17]
	v_pk_fma_f32 v[10:11], v[52:53], v[32:33], v[10:11]
	v_pk_mul_f32 v[8:9], v[8:9], v[18:19]
	v_pk_mul_f32 v[6:7], v[6:7], v[14:15]
	v_pk_mul_f32 v[8:9], v[8:9], v[10:11]
	v_cvt_pk_bf16_f32 v6, v6, v7
	v_cvt_pk_bf16_f32 v7, v8, v9
	s_andn2_b64 vcc, exec, s[6:7]
	s_mov_b64 s[2:3], -1
	global_store_dwordx2 v[82:83], v[2:3], off offset:8
	global_store_dwordx2 v[84:85], v[12:13], off offset:8
	global_store_dwordx2 v[86:87], v[4:5], off offset:8
	global_store_dwordx2 v[88:89], v[6:7], off offset:8
	s_cbranch_vccnz .LBB0_1769
	s_andn2_b64 vcc, exec, s[0:1]
	s_cbranch_vccnz .LBB0_1768
	s_barrier
	s_branch .LBB0_1768
